# rg items: select folded into one multiply, scan LDS addresses hoisted out of the item loop (verified by 512-lane simulation), gate stores issued early
# speedup vs baseline: 1.0044x; 1.0030x over previous
.LBB0_266:
	s_waitcnt vmcnt(0)
	v_cmp_gt_u32_e64 s[98:99], s45, v204
	v_mul_f32_e32 v240, 0xc1000000, v92
	v_mul_f32_e32 v241, 0xc1000000, v93
	v_mul_f32_e32 v242, 0xc1000000, v94
	v_mul_f32_e32 v243, 0xc1000000, v95
	v_mul_f32_e32 v244, 0xc1000000, v96
	v_mul_f32_e32 v245, 0xc1000000, v97
	v_mul_f32_e32 v246, 0xc1000000, v98
	v_mul_f32_e32 v247, 0xc1000000, v99
	v_cndmask_b32_e64 v240, 1.0, v240, s[98:99]
	v_cndmask_b32_e64 v241, 1.0, v241, s[98:99]
	v_cndmask_b32_e64 v242, 1.0, v242, s[98:99]
	v_cndmask_b32_e64 v243, 1.0, v243, s[98:99]
	v_cndmask_b32_e64 v244, 1.0, v244, s[98:99]
	v_cndmask_b32_e64 v245, 1.0, v245, s[98:99]
	v_cndmask_b32_e64 v246, 1.0, v246, s[98:99]
	v_cndmask_b32_e64 v247, 1.0, v247, s[98:99]
	v_and_b32_e32 v186, 63, v204
	v_bfe_u32 v187, v204, 6, 1
	v_lshl_or_b32 v186, v187, 12, v186
	v_mul_u32_u24_e32 v187, 63, v187
	v_lshrrev_b32_e32 v188, 7, v204
	v_lshlrev_b32_e32 v188, 4, v188
	v_or_b32_e32 v170, 0, v188
	v_xor_b32_e32 v170, v187, v170
	v_lshl_add_u32 v170, v170, 6, v186
	v_lshlrev_b32_e32 v170, 2, v170
	v_or_b32_e32 v171, 1, v188
	v_xor_b32_e32 v171, v187, v171
	v_lshl_add_u32 v171, v171, 6, v186
	v_lshlrev_b32_e32 v171, 2, v171
	v_or_b32_e32 v172, 2, v188
	v_xor_b32_e32 v172, v187, v172
	v_lshl_add_u32 v172, v172, 6, v186
	v_lshlrev_b32_e32 v172, 2, v172
	v_or_b32_e32 v173, 3, v188
	v_xor_b32_e32 v173, v187, v173
	v_lshl_add_u32 v173, v173, 6, v186
	v_lshlrev_b32_e32 v173, 2, v173
	v_or_b32_e32 v174, 4, v188
	v_xor_b32_e32 v174, v187, v174
	v_lshl_add_u32 v174, v174, 6, v186
	v_lshlrev_b32_e32 v174, 2, v174
	v_or_b32_e32 v175, 5, v188
	v_xor_b32_e32 v175, v187, v175
	v_lshl_add_u32 v175, v175, 6, v186
	v_lshlrev_b32_e32 v175, 2, v175
	v_or_b32_e32 v176, 6, v188
	v_xor_b32_e32 v176, v187, v176
	v_lshl_add_u32 v176, v176, 6, v186
	v_lshlrev_b32_e32 v176, 2, v176
	v_or_b32_e32 v177, 7, v188
	v_xor_b32_e32 v177, v187, v177
	v_lshl_add_u32 v177, v177, 6, v186
	v_lshlrev_b32_e32 v177, 2, v177
	v_or_b32_e32 v178, 8, v188
	v_xor_b32_e32 v178, v187, v178
	v_lshl_add_u32 v178, v178, 6, v186
	v_lshlrev_b32_e32 v178, 2, v178
	v_or_b32_e32 v179, 9, v188
	v_xor_b32_e32 v179, v187, v179
	v_lshl_add_u32 v179, v179, 6, v186
	v_lshlrev_b32_e32 v179, 2, v179
	v_or_b32_e32 v180, 10, v188
	v_xor_b32_e32 v180, v187, v180
	v_lshl_add_u32 v180, v180, 6, v186
	v_lshlrev_b32_e32 v180, 2, v180
	v_or_b32_e32 v181, 11, v188
	v_xor_b32_e32 v181, v187, v181
	v_lshl_add_u32 v181, v181, 6, v186
	v_lshlrev_b32_e32 v181, 2, v181
	v_or_b32_e32 v182, 12, v188
	v_xor_b32_e32 v182, v187, v182
	v_lshl_add_u32 v182, v182, 6, v186
	v_lshlrev_b32_e32 v182, 2, v182
	v_or_b32_e32 v183, 13, v188
	v_xor_b32_e32 v183, v187, v183
	v_lshl_add_u32 v183, v183, 6, v186
	v_lshlrev_b32_e32 v183, 2, v183
	v_or_b32_e32 v184, 14, v188
	v_xor_b32_e32 v184, v187, v184
	v_lshl_add_u32 v184, v184, 6, v186
	v_lshlrev_b32_e32 v184, 2, v184
	v_or_b32_e32 v185, 15, v188
	v_xor_b32_e32 v185, v187, v185
	v_lshl_add_u32 v185, v185, 6, v186
	v_lshlrev_b32_e32 v185, 2, v185
	v_mov_b32_e32 v68, 0
	s_mov_b32 s10, s94
	s_mov_b32 s11, s3
	s_mov_b32 s69, s97
	v_mov_b32_e32 v69, v68
	v_mov_b32_e32 v70, v68
	v_mov_b32_e32 v71, v68
	v_mov_b32_e32 v72, v68
	v_mov_b32_e32 v73, v68
	v_mov_b32_e32 v74, v68
	v_mov_b32_e32 v75, v68
	v_mov_b32_e32 v100, v68
	v_mov_b32_e32 v101, v68
	v_mov_b32_e32 v102, v68
	v_mov_b32_e32 v103, v68
	v_mov_b32_e32 v104, v68
	v_mov_b32_e32 v105, v68
	v_mov_b32_e32 v106, v68
	v_mov_b32_e32 v107, v68
	s_branch .LBB0_269

.LBB0_281:
	v_mov_b32_e32 v0, v204
	s_nop 0
	v_and_b32_e32 v3, 0xffff0000, v40
	v_lshlrev_b32_e32 v2, 3, v0
	v_and_b32_e32 v116, 56, v2
	v_lshlrev_b32_e32 v2, 16, v40
	v_pk_fma_f32 v[2:3], v[32:33], v[2:3], v[48:49]
	v_lshlrev_b32_e32 v108, 16, v24
	v_and_b32_e32 v109, 0xffff0000, v24
	v_pk_fma_f32 v[2:3], v[8:9], v[108:109], v[2:3]
	v_lshlrev_b32_e32 v108, 16, v52
	v_and_b32_e32 v109, 0xffff0000, v52
	v_pk_fma_f32 v[2:3], v[12:13], v[108:109], v[2:3]
	v_lshlrev_b32_e32 v108, 16, v56
	v_and_b32_e32 v109, 0xffff0000, v56
	v_pk_fma_f32 v[108:109], v[16:17], v[108:109], v[2:3]
	v_lshlrev_b32_e32 v2, 16, v42
	v_and_b32_e32 v3, 0xffff0000, v42
	v_pk_fma_f32 v[2:3], v[28:29], v[2:3], v[44:45]
	v_lshlrev_b32_e32 v110, 16, v26
	v_and_b32_e32 v111, 0xffff0000, v26
	v_pk_fma_f32 v[2:3], v[4:5], v[110:111], v[2:3]
	v_lshlrev_b32_e32 v110, 16, v54
	v_and_b32_e32 v111, 0xffff0000, v54
	v_pk_fma_f32 v[2:3], v[20:21], v[110:111], v[2:3]
	v_lshlrev_b32_e32 v110, 16, v58
	v_and_b32_e32 v111, 0xffff0000, v58
	v_pk_fma_f32 v[112:113], v[36:37], v[110:111], v[2:3]
	v_lshlrev_b32_e32 v2, 16, v41
	v_and_b32_e32 v3, 0xffff0000, v41
	v_pk_fma_f32 v[2:3], v[34:35], v[2:3], v[50:51]
	v_lshlrev_b32_e32 v110, 16, v25
	v_and_b32_e32 v111, 0xffff0000, v25
	v_pk_fma_f32 v[2:3], v[10:11], v[110:111], v[2:3]
	v_lshlrev_b32_e32 v110, 16, v53
	v_and_b32_e32 v111, 0xffff0000, v53
	v_pk_fma_f32 v[2:3], v[14:15], v[110:111], v[2:3]
	v_lshlrev_b32_e32 v110, 16, v57
	v_and_b32_e32 v111, 0xffff0000, v57
	v_pk_fma_f32 v[110:111], v[18:19], v[110:111], v[2:3]
	v_lshlrev_b32_e32 v2, 16, v43
	v_and_b32_e32 v3, 0xffff0000, v43
	v_pk_fma_f32 v[2:3], v[30:31], v[2:3], v[46:47]
	v_lshlrev_b32_e32 v114, 16, v27
	v_and_b32_e32 v115, 0xffff0000, v27
	v_pk_fma_f32 v[2:3], v[6:7], v[114:115], v[2:3]
	v_lshlrev_b32_e32 v114, 16, v55
	v_and_b32_e32 v115, 0xffff0000, v55
	v_pk_fma_f32 v[2:3], v[22:23], v[114:115], v[2:3]
	v_lshlrev_b32_e32 v114, 16, v59
	v_and_b32_e32 v115, 0xffff0000, v59
	v_pk_fma_f32 v[114:115], v[38:39], v[114:115], v[2:3]
	v_ashrrev_i32_e32 v3, 3, v0
	v_lshl_add_u32 v117, v3, 8, 0
	v_lshl_add_u32 v118, v116, 2, v117
	ds_write_b128 v118, v[108:111]
	ds_write_b128 v118, v[112:115] offset:16
	v_cvt_pk_bf16_f32 v108, v108, v109
	v_cvt_pk_bf16_f32 v109, v110, v111
	v_cvt_pk_bf16_f32 v110, v112, v113
	v_mul_lo_u32 v3, v3, s67
	v_lshlrev_b32_e32 v112, 1, v116
	v_and_b32_e32 v127, 15, v0
	v_cvt_pk_bf16_f32 v111, v114, v115
	v_add3_u32 v3, v117, v3, v112
	v_and_b32_e32 v2, 48, v0
	ds_write_b128 v3, v[108:111] offset:16384
	v_mul_u32_u24_e32 v3, 0x90, v127
	v_add3_u32 v3, 0, v2, v3
	s_waitcnt lgkmcnt(0)
	s_barrier
	ds_read_b128 v[108:111], v3 offset:16384
	ds_read_b128 v[112:115], v3 offset:16448
	ds_read_b128 v[120:123], v3 offset:18688
	ds_read_b128 v[128:131], v3 offset:18752
	s_waitcnt lgkmcnt(1)
	v_mfma_f32_16x16x32_bf16 v[132:135], v[60:63], v[120:123], 0
	s_add_i32 s2, 0, 0xe400
	v_cmp_gt_u32_e32 vcc, s45, v0
	v_lshlrev_b32_e32 v127, 8, v127
	v_mfma_f32_16x16x32_bf16 v[136:139], v[76:79], v[120:123], 0
	ds_read_b128 v[120:123], v3 offset:20992
	ds_read_b128 v[140:143], v3 offset:21056
	v_mfma_f32_16x16x32_bf16 v[116:119], v[60:63], v[108:111], 0
	v_mfma_f32_16x16x32_bf16 v[108:111], v[76:79], v[108:111], 0
	s_waitcnt lgkmcnt(1)
	v_mfma_f32_16x16x32_bf16 v[144:147], v[60:63], v[120:123], 0
	v_mfma_f32_16x16x32_bf16 v[148:151], v[76:79], v[120:123], 0
	ds_read_b128 v[120:123], v3 offset:23296
	ds_read_b128 v[154:157], v3 offset:23360
	v_mov_b32_e32 v3, s2
	v_mfma_f32_16x16x32_bf16 v[166:169], v[64:67], v[112:115], v[116:119]
	s_waitcnt lgkmcnt(1)
	v_mfma_f32_16x16x32_bf16 v[158:161], v[60:63], v[120:123], 0
	v_mfma_f32_16x16x32_bf16 v[162:165], v[76:79], v[120:123], 0
	v_mfma_f32_16x16x32_bf16 v[120:123], v[80:83], v[112:115], v[108:111]
	v_mfma_f32_16x16x32_bf16 v[132:135], v[64:67], v[128:131], v[132:135]
	v_mfma_f32_16x16x32_bf16 v[116:119], v[80:83], v[128:131], v[136:139]
	s_nop 5
	v_add_f32_e32 v122, v90, v122
	v_mul_f32_e32 v122, 0xbfb8aa3b, v122
	v_exp_f32_e32 v122, v122
	v_mfma_f32_16x16x32_bf16 v[128:131], v[64:67], v[140:143], v[144:147]
	v_add_f32_e32 v123, v91, v123
	v_mul_f32_e32 v123, 0xbfb8aa3b, v123
	v_exp_f32_e32 v123, v123
	v_mfma_f32_16x16x32_bf16 v[112:115], v[80:83], v[140:143], v[148:151]
	v_mov_b32_e32 v140, s73
	v_cndmask_b32_e32 v3, v3, v140, vcc
	v_lshlrev_b32_e32 v140, 7, v0
	v_and_b32_e32 v140, 0x4000, v140
	v_add3_u32 v3, v3, v140, v127
	v_add_f32_e32 v140, v84, v166
	v_mul_f32_e32 v140, 0xbfb8aa3b, v140
	v_add_f32_e32 v141, v85, v167
	v_exp_f32_e32 v140, v140
	v_mul_f32_e32 v141, 0xbfb8aa3b, v141
	v_exp_f32_e32 v141, v141
	v_lshlrev_b32_e32 v127, 1, v0
	v_and_b32_e32 v127, 0x80, v127
	v_add_f32_e32 v140, 1.0, v140
	v_rcp_f32_e32 v140, v140
	v_add3_u32 v2, v3, v127, v2
	v_add_f32_e32 v3, 1.0, v141
	v_add_f32_e32 v141, v86, v168
	v_mul_f32_e32 v141, 0xbfb8aa3b, v141
	v_rcp_f32_e32 v3, v3
	v_exp_f32_e32 v141, v141
	v_add_f32_e32 v142, v87, v169
	v_mul_f32_e32 v142, 0xbfb8aa3b, v142

	v_exp_f32_e32 v142, v142

	v_mul_f32_e32 v140, v240, v140

	v_add_f32_e32 v141, 1.0, v141

	v_rcp_f32_e32 v143, v141
	v_mul_f32_e32 v141, v241, v3
	v_add_f32_e32 v3, 1.0, v142
	v_rcp_f32_e32 v3, v3


	v_mul_f32_e32 v142, v242, v143


	v_mul_f32_e32 v143, v243, v3
	v_add_f32_e32 v3, v84, v132
	v_mul_f32_e32 v3, 0xbfb8aa3b, v3
	v_exp_f32_e32 v3, v3
	v_add_f32_e32 v127, v85, v133
	v_mul_f32_e32 v127, 0xbfb8aa3b, v127
	v_exp_f32_e32 v127, v127
	v_add_f32_e32 v3, 1.0, v3
	v_rcp_f32_e32 v3, v3
	v_add_f32_e32 v133, v86, v134
	v_add_f32_e32 v127, 1.0, v127
	v_mul_f32_e32 v133, 0xbfb8aa3b, v133
	v_rcp_f32_e32 v127, v127
	v_exp_f32_e32 v133, v133
	v_add_f32_e32 v134, v87, v135
	v_mul_f32_e32 v134, 0xbfb8aa3b, v134

	v_exp_f32_e32 v134, v134

	v_mul_f32_e32 v132, v240, v3

	v_add_f32_e32 v133, 1.0, v133

	v_rcp_f32_e32 v135, v133
	v_mul_f32_e32 v133, v241, v127
	v_add_f32_e32 v3, 1.0, v134
	v_rcp_f32_e32 v3, v3


	v_mul_f32_e32 v134, v242, v135


	v_mul_f32_e32 v135, v243, v3
	v_add_f32_e32 v3, v84, v128
	v_mul_f32_e32 v3, 0xbfb8aa3b, v3
	v_exp_f32_e32 v3, v3
	v_add_f32_e32 v127, v85, v129
	v_mul_f32_e32 v127, 0xbfb8aa3b, v127
	v_exp_f32_e32 v127, v127
	v_add_f32_e32 v3, 1.0, v3
	v_rcp_f32_e32 v3, v3
	v_add_f32_e32 v129, v86, v130
	v_add_f32_e32 v127, 1.0, v127
	v_mul_f32_e32 v129, 0xbfb8aa3b, v129
	v_rcp_f32_e32 v127, v127
	v_exp_f32_e32 v129, v129
	v_add_f32_e32 v130, v87, v131
	v_mul_f32_e32 v130, 0xbfb8aa3b, v130

	v_exp_f32_e32 v130, v130

	v_mul_f32_e32 v128, v240, v3

	v_add_f32_e32 v129, 1.0, v129

	v_rcp_f32_e32 v131, v129
	v_mul_f32_e32 v129, v241, v127
	v_add_f32_e32 v3, 1.0, v130
	v_rcp_f32_e32 v3, v3
	s_waitcnt lgkmcnt(0)
	v_mfma_f32_16x16x32_bf16 v[136:139], v[64:67], v[154:157], v[158:161]
	ds_write_b128 v2, v[140:143]
	ds_write_b128 v2, v[132:135] offset:4096


	v_mul_f32_e32 v130, v242, v131


	v_mul_f32_e32 v131, v243, v3
	s_nop 1
	s_nop 3
	v_add_f32_e32 v3, v84, v136
	v_mul_f32_e32 v3, 0xbfb8aa3b, v3
	v_exp_f32_e32 v3, v3
	v_add_f32_e32 v127, v85, v137
	v_mul_f32_e32 v127, 0xbfb8aa3b, v127
	v_exp_f32_e32 v127, v127
	v_add_f32_e32 v3, 1.0, v3
	v_rcp_f32_e32 v3, v3
	ds_write_b128 v2, v[128:131] offset:8192
	v_add_f32_e32 v129, v86, v138
	v_add_f32_e32 v127, 1.0, v127
	v_mul_f32_e32 v129, 0xbfb8aa3b, v129
	v_rcp_f32_e32 v127, v127
	v_exp_f32_e32 v129, v129
	v_add_f32_e32 v130, v87, v139
	v_mul_f32_e32 v130, 0xbfb8aa3b, v130

	v_exp_f32_e32 v130, v130

	v_mul_f32_e32 v128, v240, v3

	v_add_f32_e32 v129, 1.0, v129

	v_rcp_f32_e32 v131, v129
	v_mul_f32_e32 v129, v241, v127
	v_add_f32_e32 v3, 1.0, v130
	v_rcp_f32_e32 v3, v3


	v_mul_f32_e32 v130, v242, v131


	v_mul_f32_e32 v131, v243, v3
	v_add_f32_e32 v3, v88, v120
	ds_write_b128 v2, v[128:131] offset:12288
	v_mul_f32_e32 v3, 0xbfb8aa3b, v3
	v_exp_f32_e32 v3, v3
	v_add_f32_e32 v120, v89, v121
	v_mul_f32_e32 v120, 0xbfb8aa3b, v120
	v_exp_f32_e32 v120, v120
	v_add_f32_e32 v3, 1.0, v3
	v_rcp_f32_e32 v3, v3
	v_add_f32_e32 v122, 1.0, v122
	v_add_f32_e32 v120, 1.0, v120
	v_rcp_f32_e32 v121, v120


	v_mul_f32_e32 v120, v244, v3


	v_rcp_f32_e32 v122, v122
	v_mul_f32_e32 v121, v245, v121
	v_add_f32_e32 v3, 1.0, v123
	v_rcp_f32_e32 v3, v3


	v_mul_f32_e32 v122, v246, v122


	v_mul_f32_e32 v123, v247, v3
	v_add_f32_e32 v3, v88, v116
	ds_write_b128 v2, v[120:123] offset:64
	v_mul_f32_e32 v3, 0xbfb8aa3b, v3
	v_exp_f32_e32 v3, v3
	v_add_f32_e32 v116, v89, v117
	v_mul_f32_e32 v116, 0xbfb8aa3b, v116
	v_exp_f32_e32 v116, v116
	v_add_f32_e32 v3, 1.0, v3
	v_rcp_f32_e32 v3, v3
	v_add_f32_e32 v118, v90, v118
	v_add_f32_e32 v116, 1.0, v116
	v_mul_f32_e32 v118, 0xbfb8aa3b, v118
	v_rcp_f32_e32 v117, v116
	v_exp_f32_e32 v118, v118
	v_add_f32_e32 v119, v91, v119
	v_mul_f32_e32 v119, 0xbfb8aa3b, v119

	v_exp_f32_e32 v119, v119

	v_mul_f32_e32 v116, v244, v3

	v_add_f32_e32 v118, 1.0, v118

	v_rcp_f32_e32 v118, v118
	v_mul_f32_e32 v117, v245, v117
	v_add_f32_e32 v3, 1.0, v119
	v_rcp_f32_e32 v3, v3


	v_mul_f32_e32 v118, v246, v118


	v_mul_f32_e32 v119, v247, v3
	v_add_f32_e32 v3, v88, v112
	ds_write_b128 v2, v[116:119] offset:4160
	v_mul_f32_e32 v3, 0xbfb8aa3b, v3
	v_exp_f32_e32 v3, v3
	v_add_f32_e32 v112, v89, v113
	v_mul_f32_e32 v112, 0xbfb8aa3b, v112
	v_exp_f32_e32 v112, v112
	v_add_f32_e32 v3, 1.0, v3
	v_rcp_f32_e32 v3, v3
	v_add_f32_e32 v114, v90, v114
	v_add_f32_e32 v112, 1.0, v112
	v_mul_f32_e32 v114, 0xbfb8aa3b, v114
	v_rcp_f32_e32 v113, v112
	v_exp_f32_e32 v114, v114
	v_add_f32_e32 v115, v91, v115
	v_mul_f32_e32 v115, 0xbfb8aa3b, v115

	v_exp_f32_e32 v115, v115

	v_mul_f32_e32 v112, v244, v3

	v_add_f32_e32 v114, 1.0, v114

	v_rcp_f32_e32 v114, v114
	v_mul_f32_e32 v113, v245, v113
	v_add_f32_e32 v3, 1.0, v115
	v_rcp_f32_e32 v3, v3
	v_mfma_f32_16x16x32_bf16 v[108:111], v[80:83], v[154:157], v[162:165]


	v_mul_f32_e32 v114, v246, v114


	v_mul_f32_e32 v115, v247, v3
	s_nop 1
	ds_write_b128 v2, v[112:115] offset:8256
	s_nop 3
	v_add_f32_e32 v3, v88, v108
	v_mul_f32_e32 v3, 0xbfb8aa3b, v3
	v_exp_f32_e32 v3, v3
	v_add_f32_e32 v108, v89, v109
	v_mul_f32_e32 v108, 0xbfb8aa3b, v108
	v_exp_f32_e32 v108, v108
	v_add_f32_e32 v3, 1.0, v3
	v_rcp_f32_e32 v3, v3
	v_add_f32_e32 v110, v90, v110
	v_add_f32_e32 v108, 1.0, v108
	v_mul_f32_e32 v110, 0xbfb8aa3b, v110
	v_rcp_f32_e32 v109, v108
	v_exp_f32_e32 v110, v110
	v_add_f32_e32 v111, v91, v111
	v_mul_f32_e32 v111, 0xbfb8aa3b, v111

	v_exp_f32_e32 v111, v111

	v_mul_f32_e32 v108, v244, v3

	v_add_f32_e32 v110, 1.0, v110

	v_rcp_f32_e32 v110, v110
	v_mul_f32_e32 v109, v245, v109
	v_add_f32_e32 v3, 1.0, v111
	v_rcp_f32_e32 v3, v3


	v_mul_f32_e32 v110, v246, v110


	v_mul_f32_e32 v111, v247, v3
	ds_write_b128 v2, v[108:111] offset:12352
	v_lshlrev_b32_e32 v3, 2, v0
	v_lshlrev_b32_e32 v108, 4, v0


	v_and_b32_e32 v2, 60, v3
	v_and_b32_e32 v109, 0xffffc000, v108
	v_lshlrev_b32_e32 v2, 2, v2
	v_add_u32_e32 v109, 0, v109
	v_and_b32_e32 v108, 0x3f00, v108
	v_add3_u32 v128, v109, v108, v2
	s_waitcnt lgkmcnt(0)
	s_barrier
	ds_read_b128 v[120:123], v128 offset:25600
	ds_read_b128 v[112:115], v128 offset:58368
	v_add_u32_e32 v127, 0, v2
	v_add_u32_e32 v129, v127, v108
	ds_read_b128 v[116:119], v129
	s_waitcnt lgkmcnt(2)
	v_mul_f32_e32 v108, 0x3fb8aa3b, v120
	v_exp_f32_e32 v108, v108
	v_add_f32_e32 v109, v120, v120
	v_cmp_nlt_f32_e32 vcc, s75, v109
	s_and_saveexec_b64 s[8:9], vcc
	s_xor_b64 s[8:9], exec, s[8:9]
	v_fma_f32 v120, -v108, v108, 1.0
	s_andn2_saveexec_b64 s[8:9], s[8:9]
	v_fmamk_f32 v110, v109, 0x3c088889, v125
	v_fmaak_f32 v110, v109, v110, 0x3e2aaaab
	v_fma_f32 v110, v109, v110, 0.5
	v_fma_f32 v110, v109, v110, 1.0
	v_mul_f32_e64 v120, v110, -v109
	s_or_b64 exec, exec, s[8:9]
	v_mul_f32_e32 v109, 0x3fb8aa3b, v121
	v_exp_f32_e32 v109, v109
	v_add_f32_e32 v110, v121, v121
	v_cmp_nlt_f32_e32 vcc, s75, v110
	s_and_saveexec_b64 s[8:9], vcc
	s_xor_b64 s[8:9], exec, s[8:9]
	v_fma_f32 v121, -v109, v109, 1.0
	s_andn2_saveexec_b64 s[8:9], s[8:9]
	v_fmamk_f32 v111, v110, 0x3c088889, v125
	v_fmaak_f32 v111, v110, v111, 0x3e2aaaab
	v_fma_f32 v111, v110, v111, 0.5
	v_fma_f32 v111, v110, v111, 1.0
	v_mul_f32_e64 v121, v111, -v110
	s_or_b64 exec, exec, s[8:9]
	v_mul_f32_e32 v110, 0x3fb8aa3b, v122
	v_exp_f32_e32 v110, v110
	v_add_f32_e32 v111, v122, v122
	v_cmp_nlt_f32_e32 vcc, s75, v111
	s_and_saveexec_b64 s[8:9], vcc
	s_xor_b64 s[8:9], exec, s[8:9]
	v_fma_f32 v122, -v110, v110, 1.0
	s_andn2_saveexec_b64 s[8:9], s[8:9]
	v_fmamk_f32 v122, v111, 0x3c088889, v125
	v_fmaak_f32 v122, v111, v122, 0x3e2aaaab
	v_fma_f32 v122, v111, v122, 0.5
	v_fma_f32 v122, v111, v122, 1.0
	v_mul_f32_e64 v122, v122, -v111
	s_or_b64 exec, exec, s[8:9]
	v_mul_f32_e32 v111, 0x3fb8aa3b, v123
	v_exp_f32_e32 v111, v111
	v_add_f32_e32 v130, v123, v123
	v_cmp_nlt_f32_e32 vcc, s75, v130
	s_and_saveexec_b64 s[8:9], vcc
	s_xor_b64 s[8:9], exec, s[8:9]
	v_fma_f32 v123, -v111, v111, 1.0
	s_andn2_saveexec_b64 s[8:9], s[8:9]
	v_fmamk_f32 v123, v130, 0x3c088889, v125
	v_fmaak_f32 v123, v130, v123, 0x3e2aaaab
	v_fma_f32 v123, v130, v123, 0.5
	v_fma_f32 v123, v130, v123, 1.0
	v_mul_f32_e64 v123, v123, -v130
	s_or_b64 exec, exec, s[8:9]
	v_max_f32_e32 v120, v120, v120
	v_max_f32_e32 v120, 0, v120
	v_sqrt_f32_e32 v120, v120
	v_max_f32_e32 v121, v121, v121
	v_max_f32_e32 v121, 0, v121
	v_sqrt_f32_e32 v121, v121
	s_waitcnt lgkmcnt(1)
	v_mul_f32_e32 v112, v112, v120
	s_waitcnt lgkmcnt(0)
	v_mul_f32_e32 v112, v116, v112
	v_max_f32_e32 v116, v122, v122
	v_max_f32_e32 v120, v123, v123
	v_max_f32_e32 v116, 0, v116
	v_max_f32_e32 v120, 0, v120
	v_sqrt_f32_e32 v116, v116
	v_sqrt_f32_e32 v120, v120
	v_mul_f32_e32 v113, v113, v121
	v_mul_f32_e32 v113, v117, v113
	v_mul_f32_e32 v114, v114, v116
	v_mul_f32_e32 v115, v115, v120
	v_mul_f32_e32 v114, v118, v114
	v_mul_f32_e32 v115, v119, v115
	ds_write_b128 v128, v[108:111] offset:25600
	ds_write_b128 v128, v[112:115] offset:58368
	v_add_u32_e32 v108, 0x800, v3
	v_and_b32_e32 v109, 0x3ffff000, v108
	v_and_b32_e32 v108, 0xfc0, v108
	v_lshl_add_u32 v109, v109, 2, 0
	v_lshlrev_b32_e32 v108, 2, v108
	v_add3_u32 v130, v109, v108, v2
	ds_read_b128 v[120:123], v130 offset:25600
	ds_read_b128 v[112:115], v130 offset:58368
	v_add_u32_e32 v108, v127, v108
	ds_read_b128 v[116:119], v108
	s_waitcnt lgkmcnt(2)
	v_mul_f32_e32 v108, 0x3fb8aa3b, v120
	v_exp_f32_e32 v108, v108
	v_add_f32_e32 v109, v120, v120
	v_cmp_nlt_f32_e32 vcc, s75, v109
	s_and_saveexec_b64 s[8:9], vcc
	s_xor_b64 s[8:9], exec, s[8:9]
	v_fma_f32 v120, -v108, v108, 1.0
	s_andn2_saveexec_b64 s[8:9], s[8:9]
	v_fmamk_f32 v110, v109, 0x3c088889, v125
	v_fmaak_f32 v110, v109, v110, 0x3e2aaaab
	v_fma_f32 v110, v109, v110, 0.5
	v_fma_f32 v110, v109, v110, 1.0
	v_mul_f32_e64 v120, v110, -v109
	s_or_b64 exec, exec, s[8:9]
	v_mul_f32_e32 v109, 0x3fb8aa3b, v121
	v_exp_f32_e32 v109, v109
	v_add_f32_e32 v110, v121, v121
	v_cmp_nlt_f32_e32 vcc, s75, v110
	s_and_saveexec_b64 s[8:9], vcc
	s_xor_b64 s[8:9], exec, s[8:9]
	v_fma_f32 v121, -v109, v109, 1.0
	s_andn2_saveexec_b64 s[8:9], s[8:9]
	v_fmamk_f32 v111, v110, 0x3c088889, v125
	v_fmaak_f32 v111, v110, v111, 0x3e2aaaab
	v_fma_f32 v111, v110, v111, 0.5
	v_fma_f32 v111, v110, v111, 1.0
	v_mul_f32_e64 v121, v111, -v110
	s_or_b64 exec, exec, s[8:9]
	v_mul_f32_e32 v110, 0x3fb8aa3b, v122
	v_exp_f32_e32 v110, v110
	v_add_f32_e32 v111, v122, v122
	v_cmp_nlt_f32_e32 vcc, s75, v111
	s_and_saveexec_b64 s[8:9], vcc
	s_xor_b64 s[8:9], exec, s[8:9]
	v_fma_f32 v122, -v110, v110, 1.0
	s_andn2_saveexec_b64 s[8:9], s[8:9]
	v_fmamk_f32 v122, v111, 0x3c088889, v125
	v_fmaak_f32 v122, v111, v122, 0x3e2aaaab
	v_fma_f32 v122, v111, v122, 0.5
	v_fma_f32 v122, v111, v122, 1.0
	v_mul_f32_e64 v122, v122, -v111
	s_or_b64 exec, exec, s[8:9]
	v_mul_f32_e32 v111, 0x3fb8aa3b, v123
	v_exp_f32_e32 v111, v111
	v_add_f32_e32 v131, v123, v123
	v_cmp_nlt_f32_e32 vcc, s75, v131
	s_and_saveexec_b64 s[8:9], vcc
	s_xor_b64 s[8:9], exec, s[8:9]
	v_fma_f32 v123, -v111, v111, 1.0
	s_andn2_saveexec_b64 s[8:9], s[8:9]
	v_fmamk_f32 v123, v131, 0x3c088889, v125
	v_fmaak_f32 v123, v131, v123, 0x3e2aaaab
	v_fma_f32 v123, v131, v123, 0.5
	v_fma_f32 v123, v131, v123, 1.0
	v_mul_f32_e64 v123, v123, -v131
	s_or_b64 exec, exec, s[8:9]
	v_max_f32_e32 v120, v120, v120
	v_max_f32_e32 v120, 0, v120
	v_sqrt_f32_e32 v120, v120
	v_max_f32_e32 v121, v121, v121
	v_max_f32_e32 v121, 0, v121
	v_sqrt_f32_e32 v121, v121
	s_waitcnt lgkmcnt(1)
	v_mul_f32_e32 v112, v112, v120
	s_waitcnt lgkmcnt(0)
	v_mul_f32_e32 v112, v116, v112
	v_max_f32_e32 v116, v122, v122
	v_max_f32_e32 v120, v123, v123
	v_max_f32_e32 v116, 0, v116
	v_max_f32_e32 v120, 0, v120
	v_sqrt_f32_e32 v116, v116
	v_sqrt_f32_e32 v120, v120
	v_mul_f32_e32 v113, v113, v121
	v_mul_f32_e32 v113, v117, v113
	v_mul_f32_e32 v114, v114, v116
	v_mul_f32_e32 v115, v115, v120
	v_mul_f32_e32 v114, v118, v114
	v_mul_f32_e32 v115, v119, v115
	ds_write_b128 v130, v[108:111] offset:25600
	ds_write_b128 v130, v[112:115] offset:58368
	ds_read_b128 v[120:123], v128 offset:41984
	v_add_u32_e32 v130, 0xe400, v128
	ds_read_b128 v[112:115], v130 offset:16384
	ds_read_b128 v[116:119], v129
	s_waitcnt lgkmcnt(2)
	v_mul_f32_e32 v108, 0x3fb8aa3b, v120
	v_exp_f32_e32 v108, v108
	v_add_f32_e32 v109, v120, v120
	v_cmp_nlt_f32_e32 vcc, s75, v109
	s_and_saveexec_b64 s[8:9], vcc
	s_xor_b64 s[8:9], exec, s[8:9]
	v_fma_f32 v120, -v108, v108, 1.0
	s_andn2_saveexec_b64 s[8:9], s[8:9]
	v_fmamk_f32 v110, v109, 0x3c088889, v125
	v_fmaak_f32 v110, v109, v110, 0x3e2aaaab
	v_fma_f32 v110, v109, v110, 0.5
	v_fma_f32 v110, v109, v110, 1.0
	v_mul_f32_e64 v120, v110, -v109
	s_or_b64 exec, exec, s[8:9]
	v_mul_f32_e32 v109, 0x3fb8aa3b, v121
	v_exp_f32_e32 v109, v109
	v_add_f32_e32 v110, v121, v121
	v_cmp_nlt_f32_e32 vcc, s75, v110
	s_and_saveexec_b64 s[8:9], vcc
	s_xor_b64 s[8:9], exec, s[8:9]
	v_fma_f32 v121, -v109, v109, 1.0
	s_andn2_saveexec_b64 s[8:9], s[8:9]
	v_fmamk_f32 v111, v110, 0x3c088889, v125
	v_fmaak_f32 v111, v110, v111, 0x3e2aaaab
	v_fma_f32 v111, v110, v111, 0.5
	v_fma_f32 v111, v110, v111, 1.0
	v_mul_f32_e64 v121, v111, -v110
	s_or_b64 exec, exec, s[8:9]
	v_mul_f32_e32 v110, 0x3fb8aa3b, v122
	v_exp_f32_e32 v110, v110
	v_add_f32_e32 v111, v122, v122
	v_cmp_nlt_f32_e32 vcc, s75, v111
	s_and_saveexec_b64 s[8:9], vcc
	s_xor_b64 s[8:9], exec, s[8:9]
	v_fma_f32 v122, -v110, v110, 1.0
	s_andn2_saveexec_b64 s[8:9], s[8:9]
	v_fmamk_f32 v122, v111, 0x3c088889, v125
	v_fmaak_f32 v122, v111, v122, 0x3e2aaaab
	v_fma_f32 v122, v111, v122, 0.5
	v_fma_f32 v122, v111, v122, 1.0
	v_mul_f32_e64 v122, v122, -v111
	s_or_b64 exec, exec, s[8:9]
	v_mul_f32_e32 v111, 0x3fb8aa3b, v123
	v_exp_f32_e32 v111, v111
	v_add_f32_e32 v129, v123, v123
	v_cmp_nlt_f32_e32 vcc, s75, v129
	s_and_saveexec_b64 s[8:9], vcc
	s_xor_b64 s[8:9], exec, s[8:9]
	v_fma_f32 v123, -v111, v111, 1.0
	s_andn2_saveexec_b64 s[8:9], s[8:9]
	v_fmamk_f32 v123, v129, 0x3c088889, v125
	v_fmaak_f32 v123, v129, v123, 0x3e2aaaab
	v_fma_f32 v123, v129, v123, 0.5
	v_fma_f32 v123, v129, v123, 1.0
	v_mul_f32_e64 v123, v123, -v129
	s_or_b64 exec, exec, s[8:9]
	v_max_f32_e32 v120, v120, v120
	v_max_f32_e32 v120, 0, v120
	v_sqrt_f32_e32 v120, v120
	v_max_f32_e32 v121, v121, v121
	v_max_f32_e32 v121, 0, v121
	v_sqrt_f32_e32 v121, v121
	s_waitcnt lgkmcnt(1)
	v_mul_f32_e32 v112, v112, v120
	s_waitcnt lgkmcnt(0)
	v_mul_f32_e32 v112, v116, v112
	v_max_f32_e32 v116, v122, v122
	v_max_f32_e32 v120, v123, v123
	v_max_f32_e32 v116, 0, v116
	v_max_f32_e32 v120, 0, v120
	v_sqrt_f32_e32 v116, v116
	v_sqrt_f32_e32 v120, v120
	v_mul_f32_e32 v113, v113, v121
	v_add_u32_e32 v3, 0x1800, v3
	v_mul_f32_e32 v114, v114, v116
	v_mul_f32_e32 v115, v115, v120
	v_mul_f32_e32 v113, v117, v113
	v_mul_f32_e32 v114, v118, v114
	v_mul_f32_e32 v115, v119, v115
	ds_write_b128 v128, v[108:111] offset:41984
	ds_write_b128 v130, v[112:115] offset:16384
	v_and_b32_e32 v108, 0x3ffff000, v3
	v_and_b32_e32 v3, 0xfc0, v3
	v_lshl_add_u32 v108, v108, 2, 0
	v_lshlrev_b32_e32 v3, 2, v3
	v_add3_u32 v2, v108, v3, v2
	ds_read_b128 v[120:123], v2 offset:25600
	ds_read_b128 v[112:115], v2 offset:58368
	v_add_u32_e32 v3, v127, v3
	ds_read_b128 v[116:119], v3
	s_waitcnt lgkmcnt(2)
	v_mul_f32_e32 v3, 0x3fb8aa3b, v120
	v_exp_f32_e32 v108, v3
	v_add_f32_e32 v109, v120, v120
	v_cmp_nlt_f32_e32 vcc, s75, v109
	s_and_saveexec_b64 s[8:9], vcc
	s_xor_b64 s[8:9], exec, s[8:9]
	v_fma_f32 v3, -v108, v108, 1.0
	s_andn2_saveexec_b64 s[8:9], s[8:9]
	v_fmamk_f32 v3, v109, 0x3c088889, v125
	v_fmaak_f32 v3, v109, v3, 0x3e2aaaab
	v_fma_f32 v3, v109, v3, 0.5
	v_fma_f32 v3, v109, v3, 1.0
	v_mul_f32_e64 v3, v3, -v109
	s_or_b64 exec, exec, s[8:9]
	v_mul_f32_e32 v109, 0x3fb8aa3b, v121
	v_exp_f32_e32 v109, v109
	v_add_f32_e32 v110, v121, v121
	v_cmp_nlt_f32_e32 vcc, s75, v110
	s_and_saveexec_b64 s[8:9], vcc
	s_xor_b64 s[8:9], exec, s[8:9]
	v_fma_f32 v121, -v109, v109, 1.0
	s_andn2_saveexec_b64 s[8:9], s[8:9]
	v_fmamk_f32 v111, v110, 0x3c088889, v125
	v_fmaak_f32 v111, v110, v111, 0x3e2aaaab
	v_fma_f32 v111, v110, v111, 0.5
	v_fma_f32 v111, v110, v111, 1.0
	v_mul_f32_e64 v121, v111, -v110
	s_or_b64 exec, exec, s[8:9]
	v_mul_f32_e32 v110, 0x3fb8aa3b, v122
	v_exp_f32_e32 v110, v110
	v_add_f32_e32 v111, v122, v122
	v_cmp_nlt_f32_e32 vcc, s75, v111
	s_and_saveexec_b64 s[8:9], vcc
	s_xor_b64 s[8:9], exec, s[8:9]
	v_fma_f32 v122, -v110, v110, 1.0
	s_andn2_saveexec_b64 s[8:9], s[8:9]
	v_fmamk_f32 v120, v111, 0x3c088889, v125
	v_fmaak_f32 v120, v111, v120, 0x3e2aaaab
	v_fma_f32 v120, v111, v120, 0.5
	v_fma_f32 v120, v111, v120, 1.0
	v_mul_f32_e64 v122, v120, -v111
	s_or_b64 exec, exec, s[8:9]
	v_mul_f32_e32 v111, 0x3fb8aa3b, v123
	v_exp_f32_e32 v111, v111
	v_add_f32_e32 v120, v123, v123
	v_cmp_nlt_f32_e32 vcc, s75, v120
	s_and_saveexec_b64 s[8:9], vcc
	s_xor_b64 s[8:9], exec, s[8:9]
	v_fma_f32 v123, -v111, v111, 1.0
	s_andn2_saveexec_b64 s[8:9], s[8:9]
	v_fmamk_f32 v123, v120, 0x3c088889, v125
	v_fmaak_f32 v123, v120, v123, 0x3e2aaaab
	v_fma_f32 v123, v120, v123, 0.5
	v_fma_f32 v123, v120, v123, 1.0
	v_mul_f32_e64 v123, v123, -v120
	s_or_b64 exec, exec, s[8:9]
	v_max_f32_e32 v3, v3, v3
	v_max_f32_e32 v3, 0, v3
	v_sqrt_f32_e32 v3, v3
	v_max_f32_e32 v121, v121, v121
	v_max_f32_e32 v121, 0, v121
	v_mov_b32_e32 v120, 0
	s_waitcnt lgkmcnt(1)
	v_mul_f32_e32 v3, v112, v3
	v_sqrt_f32_e32 v112, v121
	v_max_f32_e32 v121, v122, v122
	v_max_f32_e32 v121, 0, v121
	v_sqrt_f32_e32 v121, v121
	s_waitcnt lgkmcnt(0)
	v_mul_f32_e32 v116, v116, v3
	v_mul_f32_e32 v3, v113, v112
	v_mul_f32_e32 v117, v117, v3
	v_mul_f32_e32 v3, v114, v121
	v_mul_f32_e32 v118, v118, v3
	v_max_f32_e32 v3, v123, v123
	v_max_f32_e32 v3, 0, v3
	v_sqrt_f32_e32 v3, v3
	v_ashrrev_i32_e32 v114, 7, v0
	v_and_b32_e32 v121, 0x7f, v0
	v_bfe_u32 v113, v0, 6, 1
	v_mul_f32_e32 v3, v115, v3
	v_mul_f32_e32 v119, v119, v3
	ds_write_b128 v2, v[108:111] offset:25600
	ds_write_b128 v2, v[116:119] offset:58368
	v_lshlrev_b32_e32 v2, 4, v114

	v_and_b32_e32 v112, 63, v0


	s_waitcnt lgkmcnt(0)
	s_barrier
	ds_read2st64_b32 v[116:117], v172 offset0:100 offset1:228


	ds_read2st64_b32 v[118:119], v173 offset0:100 offset1:228


	ds_read2st64_b32 v[122:123], v174 offset0:100 offset1:228


	ds_read2st64_b32 v[128:129], v175 offset0:100 offset1:228


	ds_read2st64_b32 v[130:131], v176 offset0:100 offset1:228


	ds_read2st64_b32 v[132:133], v177 offset0:100 offset1:228


	ds_read2st64_b32 v[134:135], v178 offset0:100 offset1:228


	ds_read2st64_b32 v[136:137], v179 offset0:100 offset1:228


	ds_read2st64_b32 v[138:139], v180 offset0:100 offset1:228


	ds_read2st64_b32 v[140:141], v181 offset0:100 offset1:228


	ds_read2st64_b32 v[108:109], v170 offset0:100 offset1:228


	ds_read2st64_b32 v[110:111], v171 offset0:100 offset1:228
	ds_read2st64_b32 v[142:143], v182 offset0:100 offset1:228


	s_waitcnt lgkmcnt(2)
	v_fma_f32 v109, 0, v108, v109
	ds_read2st64_b32 v[144:145], v183 offset0:100 offset1:228
	v_or_b32_e32 v115, 14, v2
	s_waitcnt lgkmcnt(2)
	v_mul_f32_e32 v108, v108, v110
	v_fmac_f32_e32 v111, v109, v110
	v_sub_u32_e32 v127, 63, v115
	v_mul_f32_e32 v108, v108, v116
	v_fmac_f32_e32 v117, v111, v116

	v_mul_f32_e32 v108, v108, v118
	v_fmac_f32_e32 v119, v117, v118

	v_mul_f32_e32 v108, v108, v122
	v_fmac_f32_e32 v123, v119, v122

	v_or_b32_e32 v2, 15, v2
	v_mul_f32_e32 v108, v108, v128
	v_fmac_f32_e32 v129, v123, v128
	ds_read2st64_b32 v[146:147], v184 offset0:100 offset1:228
	v_sub_u32_e32 v115, 63, v2
	v_mul_f32_e32 v108, v108, v130
	v_fmac_f32_e32 v131, v129, v130

	v_mul_f32_e32 v108, v108, v132
	v_fmac_f32_e32 v133, v131, v132

	v_mul_f32_e32 v108, v108, v134
	v_fmac_f32_e32 v135, v133, v134

	v_mul_f32_e32 v108, v108, v136
	v_fmac_f32_e32 v137, v135, v136
	ds_read2st64_b32 v[2:3], v185 offset0:100 offset1:228
	v_mul_f32_e32 v108, v108, v138
	v_fmac_f32_e32 v139, v137, v138
	v_mul_f32_e32 v108, v108, v140
	v_fmac_f32_e32 v141, v139, v140
	s_waitcnt lgkmcnt(3)
	v_mul_f32_e32 v108, v108, v142
	v_fmac_f32_e32 v143, v141, v142
	s_waitcnt lgkmcnt(2)
	v_mul_f32_e32 v108, v108, v144
	v_fmac_f32_e32 v145, v143, v144
	s_waitcnt lgkmcnt(1)
	v_mul_f32_e32 v108, v108, v146
	v_fmac_f32_e32 v147, v145, v146
	v_lshl_add_u32 v0, v0, 2, 0
	s_waitcnt lgkmcnt(0)
	v_mul_f32_e32 v108, v108, v2
	v_fmac_f32_e32 v3, v147, v2
	v_add_u32_e32 v2, 0x16400, v0
	v_add_u32_e32 v0, 0x16c00, v0
	ds_write_b32 v2, v108
	ds_write_b32 v0, v3
	v_cmp_lt_i32_e32 vcc, 0, v114
	v_mov_b32_e32 v0, 1.0
	v_lshl_add_u32 v2, v121, 2, 0
	s_waitcnt vmcnt(0) lgkmcnt(0)
	s_barrier
	s_and_saveexec_b64 s[8:9], vcc
	s_cbranch_execnz .LBB0_431
	s_or_b64 exec, exec, s[8:9]
	v_cmp_lt_i32_e32 vcc, 1, v114
	s_and_saveexec_b64 s[8:9], vcc
	s_cbranch_execnz .LBB0_432

.LBB0_363:
	v_mov_b32_e32 v0, v204
	v_and_b32_e32 v3, 0xffff0000, v68
	v_lshlrev_b32_e32 v2, 3, v0
	v_and_b32_e32 v116, 56, v2
	v_lshlrev_b32_e32 v2, 16, v68
	s_nop 0
	v_pk_fma_f32 v[2:3], v[32:33], v[2:3], v[48:49]
	v_lshlrev_b32_e32 v108, 16, v72
	v_and_b32_e32 v109, 0xffff0000, v72
	v_pk_fma_f32 v[2:3], v[8:9], v[108:109], v[2:3]
	v_lshlrev_b32_e32 v108, 16, v100
	v_and_b32_e32 v109, 0xffff0000, v100
	v_pk_fma_f32 v[2:3], v[12:13], v[108:109], v[2:3]
	v_lshlrev_b32_e32 v108, 16, v104
	v_and_b32_e32 v109, 0xffff0000, v104
	v_pk_fma_f32 v[108:109], v[16:17], v[108:109], v[2:3]
	v_lshlrev_b32_e32 v2, 16, v70
	v_and_b32_e32 v3, 0xffff0000, v70
	v_pk_fma_f32 v[2:3], v[28:29], v[2:3], v[44:45]
	v_lshlrev_b32_e32 v110, 16, v74
	v_and_b32_e32 v111, 0xffff0000, v74
	v_pk_fma_f32 v[2:3], v[4:5], v[110:111], v[2:3]
	v_lshlrev_b32_e32 v110, 16, v102
	v_and_b32_e32 v111, 0xffff0000, v102
	v_pk_fma_f32 v[2:3], v[20:21], v[110:111], v[2:3]
	v_lshlrev_b32_e32 v110, 16, v106
	v_and_b32_e32 v111, 0xffff0000, v106
	v_pk_fma_f32 v[112:113], v[36:37], v[110:111], v[2:3]
	v_lshlrev_b32_e32 v2, 16, v69
	v_and_b32_e32 v3, 0xffff0000, v69
	v_pk_fma_f32 v[2:3], v[34:35], v[2:3], v[50:51]
	v_lshlrev_b32_e32 v110, 16, v73
	v_and_b32_e32 v111, 0xffff0000, v73
	v_pk_fma_f32 v[2:3], v[10:11], v[110:111], v[2:3]
	v_lshlrev_b32_e32 v110, 16, v101
	v_and_b32_e32 v111, 0xffff0000, v101
	v_pk_fma_f32 v[2:3], v[14:15], v[110:111], v[2:3]
	v_lshlrev_b32_e32 v110, 16, v105
	v_and_b32_e32 v111, 0xffff0000, v105
	v_pk_fma_f32 v[110:111], v[18:19], v[110:111], v[2:3]
	v_lshlrev_b32_e32 v2, 16, v71
	v_and_b32_e32 v3, 0xffff0000, v71
	v_pk_fma_f32 v[2:3], v[30:31], v[2:3], v[46:47]
	v_lshlrev_b32_e32 v114, 16, v75
	v_and_b32_e32 v115, 0xffff0000, v75
	v_pk_fma_f32 v[2:3], v[6:7], v[114:115], v[2:3]
	v_lshlrev_b32_e32 v114, 16, v103
	v_and_b32_e32 v115, 0xffff0000, v103
	v_pk_fma_f32 v[2:3], v[22:23], v[114:115], v[2:3]
	v_lshlrev_b32_e32 v114, 16, v107
	v_and_b32_e32 v115, 0xffff0000, v107
	v_pk_fma_f32 v[114:115], v[38:39], v[114:115], v[2:3]
	v_ashrrev_i32_e32 v3, 3, v0
	v_lshl_add_u32 v117, v3, 8, 0
	v_lshl_add_u32 v118, v116, 2, v117
	ds_write_b128 v118, v[108:111]
	ds_write_b128 v118, v[112:115] offset:16
	v_cvt_pk_bf16_f32 v108, v108, v109
	v_cvt_pk_bf16_f32 v109, v110, v111
	v_cvt_pk_bf16_f32 v110, v112, v113
	v_mul_lo_u32 v3, v3, s67
	v_lshlrev_b32_e32 v112, 1, v116
	v_and_b32_e32 v127, 15, v0
	v_cvt_pk_bf16_f32 v111, v114, v115
	v_add3_u32 v3, v117, v3, v112
	v_and_b32_e32 v2, 48, v0
	ds_write_b128 v3, v[108:111] offset:16384
	v_mul_u32_u24_e32 v3, 0x90, v127
	v_add3_u32 v3, 0, v2, v3
	s_waitcnt lgkmcnt(0)
	s_barrier
	ds_read_b128 v[108:111], v3 offset:16384
	ds_read_b128 v[112:115], v3 offset:16448
	ds_read_b128 v[120:123], v3 offset:18688
	ds_read_b128 v[128:131], v3 offset:18752
	ds_read_b128 v[136:139], v3 offset:20992
	ds_read_b128 v[140:143], v3 offset:21056
	s_waitcnt lgkmcnt(5)
	v_mfma_f32_16x16x32_bf16 v[116:119], v[60:63], v[108:111], 0
	ds_read_b128 v[148:151], v3 offset:23296
	ds_read_b128 v[154:157], v3 offset:23360
	v_mov_b32_e32 v3, s2
	v_cmp_gt_u32_e32 vcc, s45, v0
	s_nop 0
	v_mfma_f32_16x16x32_bf16 v[108:111], v[76:79], v[108:111], 0
	v_lshlrev_b32_e32 v127, 8, v127
	s_waitcnt lgkmcnt(3)
	v_mfma_f32_16x16x32_bf16 v[144:147], v[60:63], v[136:139], 0
	v_mfma_f32_16x16x32_bf16 v[136:139], v[76:79], v[136:139], 0
	v_mfma_f32_16x16x32_bf16 v[162:165], v[64:67], v[112:115], v[116:119]
	s_nop 0
	v_mfma_f32_16x16x32_bf16 v[166:169], v[80:83], v[112:115], v[108:111]
	s_waitcnt lgkmcnt(2)
	v_mfma_f32_16x16x32_bf16 v[112:115], v[80:83], v[140:143], v[136:139]
	s_nop 2
	v_mov_b32_e32 v136, s73
	v_cndmask_b32_e32 v3, v3, v136, vcc
	v_lshlrev_b32_e32 v136, 7, v0
	v_and_b32_e32 v136, 0x4000, v136
	v_add3_u32 v3, v3, v136, v127
	s_nop 0
	v_add_f32_e32 v136, v84, v162
	v_mul_f32_e32 v136, 0xbfb8aa3b, v136
	v_add_f32_e32 v137, v85, v163
	v_exp_f32_e32 v136, v136
	v_mul_f32_e32 v137, 0xbfb8aa3b, v137
	v_exp_f32_e32 v137, v137
	v_lshlrev_b32_e32 v127, 1, v0
	v_and_b32_e32 v127, 0x80, v127
	v_add_f32_e32 v136, 1.0, v136
	v_rcp_f32_e32 v136, v136
	v_add3_u32 v2, v3, v127, v2
	v_add_f32_e32 v3, 1.0, v137
	v_add_f32_e32 v137, v86, v164
	v_mul_f32_e32 v137, 0xbfb8aa3b, v137
	v_rcp_f32_e32 v3, v3
	v_exp_f32_e32 v137, v137
	v_add_f32_e32 v138, v87, v165
	v_mul_f32_e32 v138, 0xbfb8aa3b, v138

	v_exp_f32_e32 v138, v138
	s_nop 0

	v_mul_f32_e32 v136, v240, v136

	v_add_f32_e32 v137, 1.0, v137
	v_mfma_f32_16x16x32_bf16 v[132:135], v[60:63], v[120:123], 0

	v_rcp_f32_e32 v139, v137
	v_mul_f32_e32 v137, v241, v3
	v_add_f32_e32 v3, 1.0, v138
	v_rcp_f32_e32 v3, v3
	s_nop 0
	v_mfma_f32_16x16x32_bf16 v[132:135], v[64:67], v[128:131], v[132:135]


	v_mul_f32_e32 v138, v242, v139


	v_mul_f32_e32 v139, v243, v3
	s_nop 1
	s_nop 3
	v_add_f32_e32 v3, v84, v132
	v_mul_f32_e32 v3, 0xbfb8aa3b, v3
	v_exp_f32_e32 v3, v3
	v_add_f32_e32 v127, v85, v133
	v_mul_f32_e32 v127, 0xbfb8aa3b, v127
	v_exp_f32_e32 v127, v127
	v_add_f32_e32 v3, 1.0, v3
	v_rcp_f32_e32 v3, v3
	v_add_f32_e32 v133, v86, v134
	v_add_f32_e32 v127, 1.0, v127
	v_mul_f32_e32 v133, 0xbfb8aa3b, v133
	v_rcp_f32_e32 v127, v127
	v_exp_f32_e32 v133, v133
	v_add_f32_e32 v134, v87, v135
	v_mul_f32_e32 v134, 0xbfb8aa3b, v134

	v_exp_f32_e32 v134, v134

	v_mul_f32_e32 v132, v240, v3

	v_add_f32_e32 v133, 1.0, v133
	v_mfma_f32_16x16x32_bf16 v[120:123], v[76:79], v[120:123], 0

	v_rcp_f32_e32 v135, v133
	v_mul_f32_e32 v133, v241, v127
	v_add_f32_e32 v3, 1.0, v134
	v_rcp_f32_e32 v3, v3
	s_nop 0
	v_mfma_f32_16x16x32_bf16 v[116:119], v[80:83], v[128:131], v[120:123]


	v_mul_f32_e32 v134, v242, v135
	v_mfma_f32_16x16x32_bf16 v[120:123], v[64:67], v[140:143], v[144:147]


	v_mul_f32_e32 v135, v243, v3
	s_waitcnt lgkmcnt(1)
	v_mfma_f32_16x16x32_bf16 v[158:161], v[60:63], v[148:151], 0
	s_nop 3
	v_add_f32_e32 v118, v90, v118
	s_nop 1
	s_nop 1
	v_add_f32_e32 v3, v84, v120
	v_mul_f32_e32 v3, 0xbfb8aa3b, v3
	v_exp_f32_e32 v3, v3
	v_add_f32_e32 v120, v85, v121
	v_mul_f32_e32 v120, 0xbfb8aa3b, v120
	v_exp_f32_e32 v120, v120
	v_add_f32_e32 v3, 1.0, v3
	v_rcp_f32_e32 v3, v3
	v_add_f32_e32 v122, v86, v122
	v_add_f32_e32 v120, 1.0, v120
	v_mul_f32_e32 v122, 0xbfb8aa3b, v122
	v_rcp_f32_e32 v121, v120
	v_exp_f32_e32 v122, v122
	v_add_f32_e32 v123, v87, v123
	v_mul_f32_e32 v123, 0xbfb8aa3b, v123

	v_exp_f32_e32 v123, v123

	v_mul_f32_e32 v120, v240, v3

	v_add_f32_e32 v122, 1.0, v122

	v_rcp_f32_e32 v122, v122
	v_mul_f32_e32 v121, v241, v121
	v_add_f32_e32 v3, 1.0, v123
	v_rcp_f32_e32 v3, v3
	s_waitcnt lgkmcnt(0)
	v_mfma_f32_16x16x32_bf16 v[128:131], v[64:67], v[154:157], v[158:161]
	ds_write_b128 v2, v[136:139]
	ds_write_b128 v2, v[132:135] offset:4096


	v_mul_f32_e32 v122, v242, v122


	v_mul_f32_e32 v123, v243, v3
	s_nop 1
	s_nop 3
	v_add_f32_e32 v3, v84, v128
	v_mul_f32_e32 v3, 0xbfb8aa3b, v3
	v_exp_f32_e32 v3, v3
	v_add_f32_e32 v127, v85, v129
	v_mul_f32_e32 v127, 0xbfb8aa3b, v127
	v_exp_f32_e32 v127, v127
	v_add_f32_e32 v3, 1.0, v3
	v_rcp_f32_e32 v3, v3
	ds_write_b128 v2, v[120:123] offset:8192
	v_add_f32_e32 v122, v86, v130
	v_add_f32_e32 v120, 1.0, v127
	v_mul_f32_e32 v122, 0xbfb8aa3b, v122
	v_rcp_f32_e32 v121, v120
	v_exp_f32_e32 v122, v122
	v_add_f32_e32 v123, v87, v131
	v_mul_f32_e32 v123, 0xbfb8aa3b, v123

	v_exp_f32_e32 v123, v123

	v_mul_f32_e32 v120, v240, v3

	v_add_f32_e32 v122, 1.0, v122

	v_rcp_f32_e32 v122, v122
	v_mul_f32_e32 v121, v241, v121
	v_add_f32_e32 v3, 1.0, v123
	v_rcp_f32_e32 v3, v3


	v_mul_f32_e32 v122, v242, v122


	v_mul_f32_e32 v123, v243, v3
	v_add_f32_e32 v3, v88, v166
	v_mul_f32_e32 v3, 0xbfb8aa3b, v3
	v_exp_f32_e32 v3, v3
	v_add_f32_e32 v127, v89, v167
	v_mul_f32_e32 v127, 0xbfb8aa3b, v127
	v_exp_f32_e32 v127, v127
	v_add_f32_e32 v3, 1.0, v3
	v_rcp_f32_e32 v3, v3
	ds_write_b128 v2, v[120:123] offset:12288
	v_add_f32_e32 v122, v90, v168
	v_add_f32_e32 v120, 1.0, v127
	v_mul_f32_e32 v122, 0xbfb8aa3b, v122
	v_rcp_f32_e32 v121, v120
	v_exp_f32_e32 v122, v122
	v_add_f32_e32 v123, v91, v169
	v_mul_f32_e32 v123, 0xbfb8aa3b, v123

	v_exp_f32_e32 v123, v123
	s_nop 0

	v_mul_f32_e32 v120, v244, v3

	v_add_f32_e32 v122, 1.0, v122

	v_rcp_f32_e32 v122, v122
	v_mul_f32_e32 v121, v245, v121
	v_add_f32_e32 v3, 1.0, v123
	v_rcp_f32_e32 v3, v3


	v_mul_f32_e32 v122, v246, v122


	v_mul_f32_e32 v123, v247, v3
	v_add_f32_e32 v3, v88, v116
	ds_write_b128 v2, v[120:123] offset:64
	v_mul_f32_e32 v3, 0xbfb8aa3b, v3
	v_exp_f32_e32 v3, v3
	v_add_f32_e32 v116, v89, v117
	v_mul_f32_e32 v116, 0xbfb8aa3b, v116
	v_exp_f32_e32 v116, v116
	v_add_f32_e32 v3, 1.0, v3
	v_rcp_f32_e32 v3, v3
	v_mul_f32_e32 v118, 0xbfb8aa3b, v118
	v_add_f32_e32 v116, 1.0, v116
	v_rcp_f32_e32 v117, v116
	v_exp_f32_e32 v118, v118
	v_add_f32_e32 v119, v91, v119
	v_mul_f32_e32 v119, 0xbfb8aa3b, v119

	v_exp_f32_e32 v119, v119

	v_mul_f32_e32 v116, v244, v3

	v_add_f32_e32 v118, 1.0, v118

	v_rcp_f32_e32 v118, v118
	v_mul_f32_e32 v117, v245, v117
	v_add_f32_e32 v3, 1.0, v119
	v_rcp_f32_e32 v3, v3


	v_mul_f32_e32 v118, v246, v118


	v_mul_f32_e32 v119, v247, v3
	v_add_f32_e32 v3, v88, v112
	ds_write_b128 v2, v[116:119] offset:4160
	v_mul_f32_e32 v3, 0xbfb8aa3b, v3
	v_exp_f32_e32 v3, v3
	v_add_f32_e32 v112, v89, v113
	v_mul_f32_e32 v112, 0xbfb8aa3b, v112
	v_exp_f32_e32 v112, v112
	v_add_f32_e32 v3, 1.0, v3
	v_rcp_f32_e32 v3, v3
	v_add_f32_e32 v114, v90, v114
	v_add_f32_e32 v112, 1.0, v112
	v_mul_f32_e32 v114, 0xbfb8aa3b, v114
	v_rcp_f32_e32 v113, v112
	v_exp_f32_e32 v114, v114
	v_add_f32_e32 v115, v91, v115
	v_mul_f32_e32 v115, 0xbfb8aa3b, v115

	v_exp_f32_e32 v115, v115

	v_mul_f32_e32 v112, v244, v3

	v_add_f32_e32 v114, 1.0, v114
	v_mfma_f32_16x16x32_bf16 v[148:151], v[76:79], v[148:151], 0

	v_rcp_f32_e32 v114, v114
	v_mul_f32_e32 v113, v245, v113
	v_add_f32_e32 v3, 1.0, v115
	v_rcp_f32_e32 v3, v3
	s_nop 0
	v_mfma_f32_16x16x32_bf16 v[108:111], v[80:83], v[154:157], v[148:151]


	v_mul_f32_e32 v114, v246, v114


	v_mul_f32_e32 v115, v247, v3
	s_nop 1
	ds_write_b128 v2, v[112:115] offset:8256
	s_nop 3
	v_add_f32_e32 v3, v88, v108
	v_mul_f32_e32 v3, 0xbfb8aa3b, v3
	v_exp_f32_e32 v3, v3
	v_add_f32_e32 v108, v89, v109
	v_mul_f32_e32 v108, 0xbfb8aa3b, v108
	v_exp_f32_e32 v108, v108
	v_add_f32_e32 v3, 1.0, v3
	v_rcp_f32_e32 v3, v3
	v_add_f32_e32 v110, v90, v110
	v_add_f32_e32 v108, 1.0, v108
	v_mul_f32_e32 v110, 0xbfb8aa3b, v110
	v_rcp_f32_e32 v109, v108
	v_exp_f32_e32 v110, v110
	v_add_f32_e32 v111, v91, v111
	v_mul_f32_e32 v111, 0xbfb8aa3b, v111

	v_exp_f32_e32 v111, v111

	v_mul_f32_e32 v108, v244, v3

	v_add_f32_e32 v110, 1.0, v110

	v_rcp_f32_e32 v110, v110
	v_mul_f32_e32 v109, v245, v109
	v_add_f32_e32 v3, 1.0, v111
	v_rcp_f32_e32 v3, v3


	v_mul_f32_e32 v110, v246, v110


	v_mul_f32_e32 v111, v247, v3
	ds_write_b128 v2, v[108:111] offset:12352
	v_lshlrev_b32_e32 v3, 2, v0
	v_lshlrev_b32_e32 v108, 4, v0


	v_and_b32_e32 v2, 60, v3
	v_and_b32_e32 v109, 0xffffc000, v108
	v_lshlrev_b32_e32 v2, 2, v2
	v_add_u32_e32 v109, 0, v109
	v_and_b32_e32 v108, 0x3f00, v108
	v_add3_u32 v128, v109, v108, v2
	s_waitcnt lgkmcnt(0)
	s_barrier
	ds_read_b128 v[120:123], v128 offset:25600
	ds_read_b128 v[112:115], v128 offset:58368
	v_add_u32_e32 v127, 0, v2
	v_add_u32_e32 v129, v127, v108
	ds_read_b128 v[116:119], v129
	s_waitcnt lgkmcnt(2)
	v_mul_f32_e32 v108, 0x3fb8aa3b, v120
	v_exp_f32_e32 v108, v108
	v_add_f32_e32 v109, v120, v120
	v_cmp_nlt_f32_e32 vcc, s75, v109
	s_and_saveexec_b64 s[6:7], vcc
	s_xor_b64 s[6:7], exec, s[6:7]
	v_fma_f32 v120, -v108, v108, 1.0
	s_andn2_saveexec_b64 s[6:7], s[6:7]
	v_fmamk_f32 v110, v109, 0x3c088889, v125
	v_fmaak_f32 v110, v109, v110, 0x3e2aaaab
	v_fma_f32 v110, v109, v110, 0.5
	v_fma_f32 v110, v109, v110, 1.0
	v_mul_f32_e64 v120, v110, -v109
	s_or_b64 exec, exec, s[6:7]
	v_mul_f32_e32 v109, 0x3fb8aa3b, v121
	v_exp_f32_e32 v109, v109
	v_add_f32_e32 v110, v121, v121
	v_cmp_nlt_f32_e32 vcc, s75, v110
	s_and_saveexec_b64 s[6:7], vcc
	s_xor_b64 s[6:7], exec, s[6:7]
	v_fma_f32 v121, -v109, v109, 1.0
	s_andn2_saveexec_b64 s[6:7], s[6:7]
	v_fmamk_f32 v111, v110, 0x3c088889, v125
	v_fmaak_f32 v111, v110, v111, 0x3e2aaaab
	v_fma_f32 v111, v110, v111, 0.5
	v_fma_f32 v111, v110, v111, 1.0
	v_mul_f32_e64 v121, v111, -v110
	s_or_b64 exec, exec, s[6:7]
	v_mul_f32_e32 v110, 0x3fb8aa3b, v122
	v_exp_f32_e32 v110, v110
	v_add_f32_e32 v111, v122, v122
	v_cmp_nlt_f32_e32 vcc, s75, v111
	s_and_saveexec_b64 s[6:7], vcc
	s_xor_b64 s[6:7], exec, s[6:7]
	v_fma_f32 v122, -v110, v110, 1.0
	s_andn2_saveexec_b64 s[6:7], s[6:7]
	v_fmamk_f32 v122, v111, 0x3c088889, v125
	v_fmaak_f32 v122, v111, v122, 0x3e2aaaab
	v_fma_f32 v122, v111, v122, 0.5
	v_fma_f32 v122, v111, v122, 1.0
	v_mul_f32_e64 v122, v122, -v111
	s_or_b64 exec, exec, s[6:7]
	v_mul_f32_e32 v111, 0x3fb8aa3b, v123
	v_exp_f32_e32 v111, v111
	v_add_f32_e32 v130, v123, v123
	v_cmp_nlt_f32_e32 vcc, s75, v130
	s_and_saveexec_b64 s[6:7], vcc
	s_xor_b64 s[6:7], exec, s[6:7]
	v_fma_f32 v123, -v111, v111, 1.0
	s_andn2_saveexec_b64 s[6:7], s[6:7]
	v_fmamk_f32 v123, v130, 0x3c088889, v125
	v_fmaak_f32 v123, v130, v123, 0x3e2aaaab
	v_fma_f32 v123, v130, v123, 0.5
	v_fma_f32 v123, v130, v123, 1.0
	v_mul_f32_e64 v123, v123, -v130
	s_or_b64 exec, exec, s[6:7]
	v_max_f32_e32 v120, v120, v120
	v_max_f32_e32 v120, 0, v120
	v_sqrt_f32_e32 v120, v120
	v_max_f32_e32 v121, v121, v121
	v_max_f32_e32 v121, 0, v121
	v_sqrt_f32_e32 v121, v121
	s_waitcnt lgkmcnt(1)
	v_mul_f32_e32 v112, v112, v120
	s_waitcnt lgkmcnt(0)
	v_mul_f32_e32 v112, v116, v112
	v_max_f32_e32 v116, v122, v122
	v_max_f32_e32 v120, v123, v123
	v_max_f32_e32 v116, 0, v116
	v_max_f32_e32 v120, 0, v120
	v_sqrt_f32_e32 v116, v116
	v_sqrt_f32_e32 v120, v120
	v_mul_f32_e32 v113, v113, v121
	v_mul_f32_e32 v113, v117, v113
	v_mul_f32_e32 v114, v114, v116
	v_mul_f32_e32 v115, v115, v120
	v_mul_f32_e32 v114, v118, v114
	v_mul_f32_e32 v115, v119, v115
	ds_write_b128 v128, v[108:111] offset:25600
	ds_write_b128 v128, v[112:115] offset:58368
	v_add_u32_e32 v108, 0x800, v3
	v_and_b32_e32 v109, 0x3ffff000, v108
	v_and_b32_e32 v108, 0xfc0, v108
	v_lshl_add_u32 v109, v109, 2, 0
	v_lshlrev_b32_e32 v108, 2, v108
	v_add3_u32 v130, v109, v108, v2
	ds_read_b128 v[120:123], v130 offset:25600
	ds_read_b128 v[112:115], v130 offset:58368
	v_add_u32_e32 v108, v127, v108
	ds_read_b128 v[116:119], v108
	s_waitcnt lgkmcnt(2)
	v_mul_f32_e32 v108, 0x3fb8aa3b, v120
	v_exp_f32_e32 v108, v108
	v_add_f32_e32 v109, v120, v120
	v_cmp_nlt_f32_e32 vcc, s75, v109
	s_and_saveexec_b64 s[6:7], vcc
	s_xor_b64 s[6:7], exec, s[6:7]
	v_fma_f32 v120, -v108, v108, 1.0
	s_andn2_saveexec_b64 s[6:7], s[6:7]
	v_fmamk_f32 v110, v109, 0x3c088889, v125
	v_fmaak_f32 v110, v109, v110, 0x3e2aaaab
	v_fma_f32 v110, v109, v110, 0.5
	v_fma_f32 v110, v109, v110, 1.0
	v_mul_f32_e64 v120, v110, -v109
	s_or_b64 exec, exec, s[6:7]
	v_mul_f32_e32 v109, 0x3fb8aa3b, v121
	v_exp_f32_e32 v109, v109
	v_add_f32_e32 v110, v121, v121
	v_cmp_nlt_f32_e32 vcc, s75, v110
	s_and_saveexec_b64 s[6:7], vcc
	s_xor_b64 s[6:7], exec, s[6:7]
	v_fma_f32 v121, -v109, v109, 1.0
	s_andn2_saveexec_b64 s[6:7], s[6:7]
	v_fmamk_f32 v111, v110, 0x3c088889, v125
	v_fmaak_f32 v111, v110, v111, 0x3e2aaaab
	v_fma_f32 v111, v110, v111, 0.5
	v_fma_f32 v111, v110, v111, 1.0
	v_mul_f32_e64 v121, v111, -v110
	s_or_b64 exec, exec, s[6:7]
	v_mul_f32_e32 v110, 0x3fb8aa3b, v122
	v_exp_f32_e32 v110, v110
	v_add_f32_e32 v111, v122, v122
	v_cmp_nlt_f32_e32 vcc, s75, v111
	s_and_saveexec_b64 s[6:7], vcc
	s_xor_b64 s[6:7], exec, s[6:7]
	v_fma_f32 v122, -v110, v110, 1.0
	s_andn2_saveexec_b64 s[6:7], s[6:7]
	v_fmamk_f32 v122, v111, 0x3c088889, v125
	v_fmaak_f32 v122, v111, v122, 0x3e2aaaab
	v_fma_f32 v122, v111, v122, 0.5
	v_fma_f32 v122, v111, v122, 1.0
	v_mul_f32_e64 v122, v122, -v111
	s_or_b64 exec, exec, s[6:7]
	v_mul_f32_e32 v111, 0x3fb8aa3b, v123
	v_exp_f32_e32 v111, v111
	v_add_f32_e32 v131, v123, v123
	v_cmp_nlt_f32_e32 vcc, s75, v131
	s_and_saveexec_b64 s[6:7], vcc
	s_xor_b64 s[6:7], exec, s[6:7]
	v_fma_f32 v123, -v111, v111, 1.0
	s_andn2_saveexec_b64 s[6:7], s[6:7]
	v_fmamk_f32 v123, v131, 0x3c088889, v125
	v_fmaak_f32 v123, v131, v123, 0x3e2aaaab
	v_fma_f32 v123, v131, v123, 0.5
	v_fma_f32 v123, v131, v123, 1.0
	v_mul_f32_e64 v123, v123, -v131
	s_or_b64 exec, exec, s[6:7]
	v_max_f32_e32 v120, v120, v120
	v_max_f32_e32 v120, 0, v120
	v_sqrt_f32_e32 v120, v120
	v_max_f32_e32 v121, v121, v121
	v_max_f32_e32 v121, 0, v121
	v_sqrt_f32_e32 v121, v121
	s_waitcnt lgkmcnt(1)
	v_mul_f32_e32 v112, v112, v120
	s_waitcnt lgkmcnt(0)
	v_mul_f32_e32 v112, v116, v112
	v_max_f32_e32 v116, v122, v122
	v_max_f32_e32 v120, v123, v123
	v_max_f32_e32 v116, 0, v116
	v_max_f32_e32 v120, 0, v120
	v_sqrt_f32_e32 v116, v116
	v_sqrt_f32_e32 v120, v120
	v_mul_f32_e32 v113, v113, v121
	v_mul_f32_e32 v113, v117, v113
	v_mul_f32_e32 v114, v114, v116
	v_mul_f32_e32 v115, v115, v120
	v_mul_f32_e32 v114, v118, v114
	v_mul_f32_e32 v115, v119, v115
	ds_write_b128 v130, v[108:111] offset:25600
	ds_write_b128 v130, v[112:115] offset:58368
	ds_read_b128 v[120:123], v128 offset:41984
	v_add_u32_e32 v130, 0xe400, v128
	ds_read_b128 v[112:115], v130 offset:16384
	ds_read_b128 v[116:119], v129
	s_waitcnt lgkmcnt(2)
	v_mul_f32_e32 v108, 0x3fb8aa3b, v120
	v_exp_f32_e32 v108, v108
	v_add_f32_e32 v109, v120, v120
	v_cmp_nlt_f32_e32 vcc, s75, v109
	s_and_saveexec_b64 s[6:7], vcc
	s_xor_b64 s[6:7], exec, s[6:7]
	v_fma_f32 v120, -v108, v108, 1.0
	s_andn2_saveexec_b64 s[6:7], s[6:7]
	v_fmamk_f32 v110, v109, 0x3c088889, v125
	v_fmaak_f32 v110, v109, v110, 0x3e2aaaab
	v_fma_f32 v110, v109, v110, 0.5
	v_fma_f32 v110, v109, v110, 1.0
	v_mul_f32_e64 v120, v110, -v109
	s_or_b64 exec, exec, s[6:7]
	v_mul_f32_e32 v109, 0x3fb8aa3b, v121
	v_exp_f32_e32 v109, v109
	v_add_f32_e32 v110, v121, v121
	v_cmp_nlt_f32_e32 vcc, s75, v110
	s_and_saveexec_b64 s[6:7], vcc
	s_xor_b64 s[6:7], exec, s[6:7]
	v_fma_f32 v121, -v109, v109, 1.0
	s_andn2_saveexec_b64 s[6:7], s[6:7]
	v_fmamk_f32 v111, v110, 0x3c088889, v125
	v_fmaak_f32 v111, v110, v111, 0x3e2aaaab
	v_fma_f32 v111, v110, v111, 0.5
	v_fma_f32 v111, v110, v111, 1.0
	v_mul_f32_e64 v121, v111, -v110
	s_or_b64 exec, exec, s[6:7]
	v_mul_f32_e32 v110, 0x3fb8aa3b, v122
	v_exp_f32_e32 v110, v110
	v_add_f32_e32 v111, v122, v122
	v_cmp_nlt_f32_e32 vcc, s75, v111
	s_and_saveexec_b64 s[6:7], vcc
	s_xor_b64 s[6:7], exec, s[6:7]
	v_fma_f32 v122, -v110, v110, 1.0
	s_andn2_saveexec_b64 s[6:7], s[6:7]
	v_fmamk_f32 v122, v111, 0x3c088889, v125
	v_fmaak_f32 v122, v111, v122, 0x3e2aaaab
	v_fma_f32 v122, v111, v122, 0.5
	v_fma_f32 v122, v111, v122, 1.0
	v_mul_f32_e64 v122, v122, -v111
	s_or_b64 exec, exec, s[6:7]
	v_mul_f32_e32 v111, 0x3fb8aa3b, v123
	v_exp_f32_e32 v111, v111
	v_add_f32_e32 v129, v123, v123
	v_cmp_nlt_f32_e32 vcc, s75, v129
	s_and_saveexec_b64 s[6:7], vcc
	s_xor_b64 s[6:7], exec, s[6:7]
	v_fma_f32 v123, -v111, v111, 1.0
	s_andn2_saveexec_b64 s[6:7], s[6:7]
	v_fmamk_f32 v123, v129, 0x3c088889, v125
	v_fmaak_f32 v123, v129, v123, 0x3e2aaaab
	v_fma_f32 v123, v129, v123, 0.5
	v_fma_f32 v123, v129, v123, 1.0
	v_mul_f32_e64 v123, v123, -v129
	s_or_b64 exec, exec, s[6:7]
	v_max_f32_e32 v120, v120, v120
	v_max_f32_e32 v120, 0, v120
	v_sqrt_f32_e32 v120, v120
	v_max_f32_e32 v121, v121, v121
	v_max_f32_e32 v121, 0, v121
	v_sqrt_f32_e32 v121, v121
	s_waitcnt lgkmcnt(1)
	v_mul_f32_e32 v112, v112, v120
	s_waitcnt lgkmcnt(0)
	v_mul_f32_e32 v112, v116, v112
	v_max_f32_e32 v116, v122, v122
	v_max_f32_e32 v120, v123, v123
	v_max_f32_e32 v116, 0, v116
	v_max_f32_e32 v120, 0, v120
	v_sqrt_f32_e32 v116, v116
	v_sqrt_f32_e32 v120, v120
	v_mul_f32_e32 v113, v113, v121
	v_add_u32_e32 v3, 0x1800, v3
	v_mul_f32_e32 v114, v114, v116
	v_mul_f32_e32 v115, v115, v120
	v_mul_f32_e32 v113, v117, v113
	v_mul_f32_e32 v114, v118, v114
	v_mul_f32_e32 v115, v119, v115
	ds_write_b128 v128, v[108:111] offset:41984
	ds_write_b128 v130, v[112:115] offset:16384
	v_and_b32_e32 v108, 0x3ffff000, v3
	v_and_b32_e32 v3, 0xfc0, v3
	v_lshl_add_u32 v108, v108, 2, 0
	v_lshlrev_b32_e32 v3, 2, v3
	v_add3_u32 v2, v108, v3, v2
	ds_read_b128 v[120:123], v2 offset:25600
	ds_read_b128 v[112:115], v2 offset:58368
	v_add_u32_e32 v3, v127, v3
	ds_read_b128 v[116:119], v3
	s_waitcnt lgkmcnt(2)
	v_mul_f32_e32 v3, 0x3fb8aa3b, v120
	v_exp_f32_e32 v108, v3
	v_add_f32_e32 v109, v120, v120
	v_cmp_nlt_f32_e32 vcc, s75, v109
	s_and_saveexec_b64 s[6:7], vcc
	s_xor_b64 s[6:7], exec, s[6:7]
	v_fma_f32 v3, -v108, v108, 1.0
	s_andn2_saveexec_b64 s[6:7], s[6:7]
	v_fmamk_f32 v3, v109, 0x3c088889, v125
	v_fmaak_f32 v3, v109, v3, 0x3e2aaaab
	v_fma_f32 v3, v109, v3, 0.5
	v_fma_f32 v3, v109, v3, 1.0
	v_mul_f32_e64 v3, v3, -v109
	s_or_b64 exec, exec, s[6:7]
	v_mul_f32_e32 v109, 0x3fb8aa3b, v121
	v_exp_f32_e32 v109, v109
	v_add_f32_e32 v110, v121, v121
	v_cmp_nlt_f32_e32 vcc, s75, v110
	s_and_saveexec_b64 s[6:7], vcc
	s_xor_b64 s[6:7], exec, s[6:7]
	v_fma_f32 v121, -v109, v109, 1.0
	s_andn2_saveexec_b64 s[6:7], s[6:7]
	v_fmamk_f32 v111, v110, 0x3c088889, v125
	v_fmaak_f32 v111, v110, v111, 0x3e2aaaab
	v_fma_f32 v111, v110, v111, 0.5
	v_fma_f32 v111, v110, v111, 1.0
	v_mul_f32_e64 v121, v111, -v110
	s_or_b64 exec, exec, s[6:7]
	v_mul_f32_e32 v110, 0x3fb8aa3b, v122
	v_exp_f32_e32 v110, v110
	v_add_f32_e32 v111, v122, v122
	v_cmp_nlt_f32_e32 vcc, s75, v111
	s_and_saveexec_b64 s[6:7], vcc
	s_xor_b64 s[6:7], exec, s[6:7]
	v_fma_f32 v122, -v110, v110, 1.0
	s_andn2_saveexec_b64 s[6:7], s[6:7]
	v_fmamk_f32 v120, v111, 0x3c088889, v125
	v_fmaak_f32 v120, v111, v120, 0x3e2aaaab
	v_fma_f32 v120, v111, v120, 0.5
	v_fma_f32 v120, v111, v120, 1.0
	v_mul_f32_e64 v122, v120, -v111
	s_or_b64 exec, exec, s[6:7]
	v_mul_f32_e32 v111, 0x3fb8aa3b, v123
	v_exp_f32_e32 v111, v111
	v_add_f32_e32 v120, v123, v123
	v_cmp_nlt_f32_e32 vcc, s75, v120
	s_and_saveexec_b64 s[6:7], vcc
	s_xor_b64 s[6:7], exec, s[6:7]
	v_fma_f32 v123, -v111, v111, 1.0
	s_andn2_saveexec_b64 s[6:7], s[6:7]
	v_fmamk_f32 v123, v120, 0x3c088889, v125
	v_fmaak_f32 v123, v120, v123, 0x3e2aaaab
	v_fma_f32 v123, v120, v123, 0.5
	v_fma_f32 v123, v120, v123, 1.0
	v_mul_f32_e64 v123, v123, -v120
	s_or_b64 exec, exec, s[6:7]
	v_max_f32_e32 v3, v3, v3
	v_max_f32_e32 v3, 0, v3
	v_sqrt_f32_e32 v3, v3
	v_max_f32_e32 v121, v121, v121
	v_max_f32_e32 v121, 0, v121
	v_mov_b32_e32 v120, 0
	s_waitcnt lgkmcnt(1)
	v_mul_f32_e32 v3, v112, v3
	v_sqrt_f32_e32 v112, v121
	v_max_f32_e32 v121, v122, v122
	v_max_f32_e32 v121, 0, v121
	v_sqrt_f32_e32 v121, v121
	s_waitcnt lgkmcnt(0)
	v_mul_f32_e32 v116, v116, v3
	v_mul_f32_e32 v3, v113, v112
	v_mul_f32_e32 v117, v117, v3
	v_mul_f32_e32 v3, v114, v121
	v_mul_f32_e32 v118, v118, v3
	v_max_f32_e32 v3, v123, v123
	v_max_f32_e32 v3, 0, v3
	v_sqrt_f32_e32 v3, v3
	v_ashrrev_i32_e32 v114, 7, v0
	v_and_b32_e32 v121, 0x7f, v0
	v_bfe_u32 v113, v0, 6, 1
	v_mul_f32_e32 v3, v115, v3
	v_mul_f32_e32 v119, v119, v3
	ds_write_b128 v2, v[108:111] offset:25600
	ds_write_b128 v2, v[116:119] offset:58368
	v_lshlrev_b32_e32 v2, 4, v114

	v_and_b32_e32 v112, 63, v0


	s_waitcnt lgkmcnt(0)
	s_barrier
	ds_read2st64_b32 v[116:117], v172 offset0:100 offset1:228


	ds_read2st64_b32 v[118:119], v173 offset0:100 offset1:228


	ds_read2st64_b32 v[122:123], v174 offset0:100 offset1:228


	ds_read2st64_b32 v[128:129], v175 offset0:100 offset1:228


	ds_read2st64_b32 v[130:131], v176 offset0:100 offset1:228


	ds_read2st64_b32 v[132:133], v177 offset0:100 offset1:228


	ds_read2st64_b32 v[134:135], v178 offset0:100 offset1:228


	ds_read2st64_b32 v[136:137], v179 offset0:100 offset1:228


	ds_read2st64_b32 v[138:139], v180 offset0:100 offset1:228


	ds_read2st64_b32 v[140:141], v181 offset0:100 offset1:228


	ds_read2st64_b32 v[108:109], v170 offset0:100 offset1:228


	ds_read2st64_b32 v[110:111], v171 offset0:100 offset1:228
	ds_read2st64_b32 v[142:143], v182 offset0:100 offset1:228


	s_waitcnt lgkmcnt(2)
	v_fma_f32 v109, 0, v108, v109
	ds_read2st64_b32 v[144:145], v183 offset0:100 offset1:228
	v_or_b32_e32 v115, 14, v2
	s_waitcnt lgkmcnt(2)
	v_mul_f32_e32 v108, v108, v110
	v_fmac_f32_e32 v111, v109, v110
	v_sub_u32_e32 v127, 63, v115
	v_mul_f32_e32 v108, v108, v116
	v_fmac_f32_e32 v117, v111, v116

	v_mul_f32_e32 v108, v108, v118
	v_fmac_f32_e32 v119, v117, v118

	v_mul_f32_e32 v108, v108, v122
	v_fmac_f32_e32 v123, v119, v122

	v_or_b32_e32 v2, 15, v2
	v_mul_f32_e32 v108, v108, v128
	v_fmac_f32_e32 v129, v123, v128
	ds_read2st64_b32 v[146:147], v184 offset0:100 offset1:228
	v_sub_u32_e32 v115, 63, v2
	v_mul_f32_e32 v108, v108, v130
	v_fmac_f32_e32 v131, v129, v130

	v_mul_f32_e32 v108, v108, v132
	v_fmac_f32_e32 v133, v131, v132

	v_mul_f32_e32 v108, v108, v134
	v_fmac_f32_e32 v135, v133, v134

	v_mul_f32_e32 v108, v108, v136
	v_fmac_f32_e32 v137, v135, v136
	ds_read2st64_b32 v[2:3], v185 offset0:100 offset1:228
	v_mul_f32_e32 v108, v108, v138
	v_fmac_f32_e32 v139, v137, v138
	v_mul_f32_e32 v108, v108, v140
	v_fmac_f32_e32 v141, v139, v140
	s_waitcnt lgkmcnt(3)
	v_mul_f32_e32 v108, v108, v142
	v_fmac_f32_e32 v143, v141, v142
	s_waitcnt lgkmcnt(2)
	v_mul_f32_e32 v108, v108, v144
	v_fmac_f32_e32 v145, v143, v144
	s_waitcnt lgkmcnt(1)
	v_mul_f32_e32 v108, v108, v146
	v_fmac_f32_e32 v147, v145, v146
	v_lshl_add_u32 v0, v0, 2, 0
	s_waitcnt lgkmcnt(0)
	v_mul_f32_e32 v108, v108, v2
	v_fmac_f32_e32 v3, v147, v2
	v_add_u32_e32 v2, 0x16400, v0
	v_add_u32_e32 v0, 0x16c00, v0
	ds_write_b32 v2, v108
	ds_write_b32 v0, v3
	v_cmp_lt_i32_e32 vcc, 0, v114
	v_mov_b32_e32 v0, 1.0
	v_lshl_add_u32 v2, v121, 2, 0
	s_waitcnt vmcnt(0) lgkmcnt(0)
	s_barrier
	s_and_saveexec_b64 s[6:7], vcc
	s_cbranch_execnz .LBB0_434
	s_or_b64 exec, exec, s[6:7]
	v_cmp_lt_i32_e32 vcc, 1, v114
	s_and_saveexec_b64 s[6:7], vcc
	s_cbranch_execnz .LBB0_435

.LBB0_609:
	s_waitcnt vmcnt(0)
	v_cmp_gt_u32_e64 s[98:99], s49, v204
	v_mul_f32_e32 v240, 0xc1000000, v88
	v_mul_f32_e32 v241, 0xc1000000, v89
	v_mul_f32_e32 v242, 0xc1000000, v90
	v_mul_f32_e32 v243, 0xc1000000, v91
	v_mul_f32_e32 v244, 0xc1000000, v92
	v_mul_f32_e32 v245, 0xc1000000, v93
	v_mul_f32_e32 v246, 0xc1000000, v94
	v_mul_f32_e32 v247, 0xc1000000, v95
	v_cndmask_b32_e64 v240, 1.0, v240, s[98:99]
	v_cndmask_b32_e64 v241, 1.0, v241, s[98:99]
	v_cndmask_b32_e64 v242, 1.0, v242, s[98:99]
	v_cndmask_b32_e64 v243, 1.0, v243, s[98:99]
	v_cndmask_b32_e64 v244, 1.0, v244, s[98:99]
	v_cndmask_b32_e64 v245, 1.0, v245, s[98:99]
	v_cndmask_b32_e64 v246, 1.0, v246, s[98:99]
	v_cndmask_b32_e64 v247, 1.0, v247, s[98:99]
	v_and_b32_e32 v192, 63, v204
	v_bfe_u32 v193, v204, 6, 1
	v_lshl_or_b32 v192, v193, 12, v192
	v_mul_u32_u24_e32 v193, 63, v193
	v_lshrrev_b32_e32 v194, 7, v204
	v_lshlrev_b32_e32 v194, 4, v194
	v_or_b32_e32 v176, 0, v194
	v_xor_b32_e32 v176, v193, v176
	v_lshl_add_u32 v176, v176, 6, v192
	v_lshlrev_b32_e32 v176, 2, v176
	v_or_b32_e32 v177, 1, v194
	v_xor_b32_e32 v177, v193, v177
	v_lshl_add_u32 v177, v177, 6, v192
	v_lshlrev_b32_e32 v177, 2, v177
	v_or_b32_e32 v178, 2, v194
	v_xor_b32_e32 v178, v193, v178
	v_lshl_add_u32 v178, v178, 6, v192
	v_lshlrev_b32_e32 v178, 2, v178
	v_or_b32_e32 v179, 3, v194
	v_xor_b32_e32 v179, v193, v179
	v_lshl_add_u32 v179, v179, 6, v192
	v_lshlrev_b32_e32 v179, 2, v179
	v_or_b32_e32 v180, 4, v194
	v_xor_b32_e32 v180, v193, v180
	v_lshl_add_u32 v180, v180, 6, v192
	v_lshlrev_b32_e32 v180, 2, v180
	v_or_b32_e32 v181, 5, v194
	v_xor_b32_e32 v181, v193, v181
	v_lshl_add_u32 v181, v181, 6, v192
	v_lshlrev_b32_e32 v181, 2, v181
	v_or_b32_e32 v182, 6, v194
	v_xor_b32_e32 v182, v193, v182
	v_lshl_add_u32 v182, v182, 6, v192
	v_lshlrev_b32_e32 v182, 2, v182
	v_or_b32_e32 v183, 7, v194
	v_xor_b32_e32 v183, v193, v183
	v_lshl_add_u32 v183, v183, 6, v192
	v_lshlrev_b32_e32 v183, 2, v183
	v_or_b32_e32 v184, 8, v194
	v_xor_b32_e32 v184, v193, v184
	v_lshl_add_u32 v184, v184, 6, v192
	v_lshlrev_b32_e32 v184, 2, v184
	v_or_b32_e32 v185, 9, v194
	v_xor_b32_e32 v185, v193, v185
	v_lshl_add_u32 v185, v185, 6, v192
	v_lshlrev_b32_e32 v185, 2, v185
	v_or_b32_e32 v186, 10, v194
	v_xor_b32_e32 v186, v193, v186
	v_lshl_add_u32 v186, v186, 6, v192
	v_lshlrev_b32_e32 v186, 2, v186
	v_or_b32_e32 v187, 11, v194
	v_xor_b32_e32 v187, v193, v187
	v_lshl_add_u32 v187, v187, 6, v192
	v_lshlrev_b32_e32 v187, 2, v187
	v_or_b32_e32 v188, 12, v194
	v_xor_b32_e32 v188, v193, v188
	v_lshl_add_u32 v188, v188, 6, v192
	v_lshlrev_b32_e32 v188, 2, v188
	v_or_b32_e32 v189, 13, v194
	v_xor_b32_e32 v189, v193, v189
	v_lshl_add_u32 v189, v189, 6, v192
	v_lshlrev_b32_e32 v189, 2, v189
	v_or_b32_e32 v190, 14, v194
	v_xor_b32_e32 v190, v193, v190
	v_lshl_add_u32 v190, v190, 6, v192
	v_lshlrev_b32_e32 v190, 2, v190
	v_or_b32_e32 v191, 15, v194
	v_xor_b32_e32 v191, v193, v191
	v_lshl_add_u32 v191, v191, 6, v192
	v_lshlrev_b32_e32 v191, 2, v191
	v_mov_b32_e32 v2, v0
	v_mov_b32_e32 v3, v0
	v_mov_b32_e32 v1, v0
	v_mov_b32_e32 v68, 0
	v_mov_b64_e32 v[114:115], v[2:3]
	v_mov_b32_e32 v150, 0
	v_readlane_b32 s12, v238, 15
	s_mov_b32 s13, s3
	s_mov_b32 s2, s97
	v_mov_b64_e32 v[112:113], v[0:1]
	v_mov_b32_e32 v69, v68
	v_mov_b32_e32 v70, v68
	v_mov_b32_e32 v71, v68
	v_mov_b32_e32 v96, v68
	v_mov_b32_e32 v97, v68
	v_mov_b32_e32 v98, v68
	v_mov_b32_e32 v99, v68
	v_mov_b32_e32 v104, v68
	v_mov_b32_e32 v105, v68
	v_mov_b32_e32 v106, v68
	v_mov_b32_e32 v107, v68
	v_mov_b32_e32 v108, v68
	v_mov_b32_e32 v109, v68
	v_mov_b32_e32 v110, v68
	v_mov_b32_e32 v111, v68
	s_branch .LBB0_612

.LBB0_624:
	s_nop 0
	v_lshlrev_b32_e32 v2, 16, v40
	v_and_b32_e32 v3, 0xffff0000, v40
	v_pk_fma_f32 v[2:3], v[36:37], v[2:3], v[48:49]
	v_lshlrev_b32_e32 v116, 16, v28
	v_and_b32_e32 v117, 0xffff0000, v28
	v_pk_fma_f32 v[2:3], v[8:9], v[116:117], v[2:3]
	v_lshlrev_b32_e32 v116, 16, v52
	v_and_b32_e32 v117, 0xffff0000, v52
	v_pk_fma_f32 v[2:3], v[12:13], v[116:117], v[2:3]
	v_lshlrev_b32_e32 v116, 16, v60
	v_and_b32_e32 v117, 0xffff0000, v60
	v_pk_fma_f32 v[116:117], v[16:17], v[116:117], v[2:3]
	v_lshlrev_b32_e32 v2, 16, v42
	v_and_b32_e32 v3, 0xffff0000, v42
	v_pk_fma_f32 v[2:3], v[24:25], v[2:3], v[44:45]
	v_lshlrev_b32_e32 v118, 16, v30
	v_and_b32_e32 v119, 0xffff0000, v30
	v_pk_fma_f32 v[2:3], v[4:5], v[118:119], v[2:3]
	v_lshlrev_b32_e32 v118, 16, v54
	v_and_b32_e32 v119, 0xffff0000, v54
	v_pk_fma_f32 v[2:3], v[20:21], v[118:119], v[2:3]
	v_lshlrev_b32_e32 v118, 16, v62
	v_and_b32_e32 v119, 0xffff0000, v62
	v_pk_fma_f32 v[120:121], v[32:33], v[118:119], v[2:3]
	v_lshlrev_b32_e32 v2, 16, v41
	v_and_b32_e32 v3, 0xffff0000, v41
	v_pk_fma_f32 v[2:3], v[38:39], v[2:3], v[50:51]
	v_lshlrev_b32_e32 v118, 16, v29
	v_and_b32_e32 v119, 0xffff0000, v29
	v_pk_fma_f32 v[2:3], v[10:11], v[118:119], v[2:3]
	v_lshlrev_b32_e32 v118, 16, v53
	v_and_b32_e32 v119, 0xffff0000, v53
	v_pk_fma_f32 v[2:3], v[14:15], v[118:119], v[2:3]
	v_lshlrev_b32_e32 v118, 16, v61
	v_and_b32_e32 v119, 0xffff0000, v61
	v_pk_fma_f32 v[118:119], v[18:19], v[118:119], v[2:3]
	v_lshlrev_b32_e32 v2, 16, v43
	v_and_b32_e32 v3, 0xffff0000, v43
	v_pk_fma_f32 v[2:3], v[26:27], v[2:3], v[46:47]
	v_lshlrev_b32_e32 v122, 16, v31
	v_and_b32_e32 v123, 0xffff0000, v31
	v_pk_fma_f32 v[2:3], v[6:7], v[122:123], v[2:3]
	v_lshlrev_b32_e32 v122, 16, v55
	v_and_b32_e32 v123, 0xffff0000, v55
	v_mov_b32_e32 v152, v204
	v_pk_fma_f32 v[2:3], v[22:23], v[122:123], v[2:3]
	v_lshlrev_b32_e32 v122, 16, v63
	v_and_b32_e32 v123, 0xffff0000, v63
	v_pk_fma_f32 v[122:123], v[34:35], v[122:123], v[2:3]
	v_lshlrev_b32_e32 v1, 3, v152
	v_ashrrev_i32_e32 v2, 3, v152
	v_and_b32_e32 v1, 56, v1
	v_lshl_add_u32 v151, v2, 8, 0
	v_lshl_add_u32 v3, v1, 2, v151
	ds_write_b128 v3, v[116:119]
	ds_write_b128 v3, v[120:123] offset:16
	v_cvt_pk_bf16_f32 v116, v116, v117
	v_cvt_pk_bf16_f32 v117, v118, v119
	v_cvt_pk_bf16_f32 v118, v120, v121
	v_mul_lo_u32 v120, v2, s1
	v_lshlrev_b32_e32 v121, 1, v1
	v_and_b32_e32 v162, 15, v152
	v_cvt_pk_bf16_f32 v119, v122, v123
	v_add3_u32 v120, v151, v120, v121
	v_and_b32_e32 v153, 48, v152
	ds_write_b128 v120, v[116:119] offset:16384
	v_mul_u32_u24_e32 v116, 0x90, v162
	v_add3_u32 v163, 0, v153, v116
	s_waitcnt lgkmcnt(0)
	s_barrier
	ds_read_b128 v[128:131], v163 offset:20992
	s_waitcnt lgkmcnt(0)
	v_mfma_f32_16x16x32_bf16 v[136:139], v[56:59], v[128:131], 0
	ds_read_b128 v[116:119], v163 offset:16384
	ds_read_b128 v[124:127], v163 offset:18688
	s_add_i32 s51, 0, 0xe400
	v_mfma_f32_16x16x32_bf16 v[140:143], v[72:75], v[128:131], 0
	ds_read_b128 v[128:131], v163 offset:23296
	v_cmp_gt_u32_e32 vcc, s49, v152
	s_waitcnt lgkmcnt(0)
	v_mfma_f32_16x16x32_bf16 v[144:147], v[56:59], v[128:131], 0
	v_mfma_f32_16x16x32_bf16 v[154:157], v[72:75], v[128:131], 0
	ds_read_b128 v[128:131], v163 offset:16448
	v_mfma_f32_16x16x32_bf16 v[120:123], v[56:59], v[116:119], 0
	v_mfma_f32_16x16x32_bf16 v[116:119], v[72:75], v[116:119], 0
	s_waitcnt lgkmcnt(0)
	v_mfma_f32_16x16x32_bf16 v[158:161], v[64:67], v[128:131], v[120:123]
	v_mfma_f32_16x16x32_bf16 v[128:131], v[76:79], v[128:131], v[116:119]
	s_nop 4
	ds_read_b128 v[116:119], v163 offset:18752
	v_mfma_f32_16x16x32_bf16 v[132:135], v[56:59], v[124:127], 0
	s_nop 0
	v_add_f32_e32 v128, v84, v128
	v_mul_f32_e32 v128, 0xbfb8aa3b, v128
	v_exp_f32_e32 v128, v128
	v_mfma_f32_16x16x32_bf16 v[124:127], v[72:75], v[124:127], 0
	v_add_f32_e32 v129, v85, v129
	v_mul_f32_e32 v129, 0xbfb8aa3b, v129
	v_exp_f32_e32 v129, v129
	s_waitcnt lgkmcnt(0)
	v_mfma_f32_16x16x32_bf16 v[132:135], v[64:67], v[116:119], v[132:135]
	v_add_f32_e32 v130, v86, v130
	v_mul_f32_e32 v130, 0xbfb8aa3b, v130
	v_add_f32_e32 v128, 1.0, v128
	v_mfma_f32_16x16x32_bf16 v[124:127], v[76:79], v[116:119], v[124:127]
	ds_read_b128 v[116:119], v163 offset:21056
	s_nop 2
	v_add_f32_e32 v132, v80, v132
	v_mul_f32_e32 v132, 0xbfb8aa3b, v132
	s_waitcnt lgkmcnt(0)
	v_mfma_f32_16x16x32_bf16 v[136:139], v[64:67], v[116:119], v[136:139]
	v_exp_f32_e32 v132, v132
	v_add_f32_e32 v133, v81, v133
	v_mul_f32_e32 v133, 0xbfb8aa3b, v133
	v_mfma_f32_16x16x32_bf16 v[120:123], v[76:79], v[116:119], v[140:143]
	ds_read_b128 v[116:119], v163 offset:23360
	v_exp_f32_e32 v133, v133
	v_add_f32_e32 v134, v82, v134
	s_waitcnt lgkmcnt(0)
	v_mfma_f32_16x16x32_bf16 v[140:143], v[64:67], v[116:119], v[144:147]
	v_mul_f32_e32 v134, 0xbfb8aa3b, v134
	s_nop 1
	v_mov_b32_e32 v144, s51
	v_mov_b32_e32 v145, s81
	v_cndmask_b32_e32 v144, v144, v145, vcc
	v_lshlrev_b32_e32 v145, 7, v152
	v_and_b32_e32 v145, 0x4000, v145
	v_lshlrev_b32_e32 v146, 8, v162
	v_add3_u32 v144, v144, v145, v146
	v_add_f32_e32 v146, v80, v158
	v_mul_f32_e32 v146, 0xbfb8aa3b, v146
	v_add_f32_e32 v147, v81, v159
	v_exp_f32_e32 v146, v146
	v_mul_f32_e32 v147, 0xbfb8aa3b, v147
	v_exp_f32_e32 v147, v147
	v_lshlrev_b32_e32 v145, 1, v152
	v_and_b32_e32 v145, 0x80, v145
	v_add_f32_e32 v146, 1.0, v146
	v_rcp_f32_e32 v146, v146
	v_add3_u32 v153, v144, v145, v153
	v_add_f32_e32 v144, 1.0, v147
	v_add_f32_e32 v147, v82, v160
	v_mul_f32_e32 v147, 0xbfb8aa3b, v147
	v_mfma_f32_16x16x32_bf16 v[116:119], v[76:79], v[116:119], v[154:157]
	v_rcp_f32_e32 v145, v144
	v_exp_f32_e32 v147, v147

	s_nop 0
	v_add_f32_e32 v154, v83, v161
	v_mul_f32_e32 v154, 0xbfb8aa3b, v154
	v_exp_f32_e32 v154, v154
	s_nop 0

	v_mul_f32_e32 v144, v240, v146

	v_add_f32_e32 v147, 1.0, v147

	v_rcp_f32_e32 v147, v147
	v_mul_f32_e32 v145, v241, v145
	v_add_f32_e32 v146, 1.0, v154
	v_rcp_f32_e32 v154, v146

	v_add_f32_e32 v132, 1.0, v132
	v_exp_f32_e32 v134, v134
	v_add_f32_e32 v135, v83, v135

	v_rcp_f32_e32 v132, v132
	v_mul_f32_e32 v135, 0xbfb8aa3b, v135
	v_mul_f32_e32 v146, v242, v147

	v_add_f32_e32 v133, 1.0, v133
	v_exp_f32_e32 v135, v135

	v_rcp_f32_e32 v133, v133
	v_mul_f32_e32 v147, v243, v154
	v_add_f32_e32 v134, 1.0, v134
	v_add_f32_e32 v136, v80, v136
	ds_write_b128 v153, v[144:147]

	v_rcp_f32_e32 v134, v134
	v_mul_f32_e32 v136, 0xbfb8aa3b, v136

	v_add_f32_e32 v135, 1.0, v135
	v_exp_f32_e32 v136, v136
	v_mul_f32_e32 v132, v240, v132

	v_rcp_f32_e32 v135, v135

	v_add_f32_e32 v137, v81, v137
	v_mul_f32_e32 v133, v241, v133

	v_mul_f32_e32 v137, 0xbfb8aa3b, v137

	v_exp_f32_e32 v137, v137
	v_add_f32_e32 v136, 1.0, v136
	v_mul_f32_e32 v134, v242, v134

	v_rcp_f32_e32 v136, v136

	v_mul_f32_e32 v135, v243, v135
	ds_write_b128 v153, v[132:135] offset:4096
	v_add_f32_e32 v132, 1.0, v137
	v_rcp_f32_e32 v133, v132

	v_add_f32_e32 v135, v82, v138

	v_mul_f32_e32 v135, 0xbfb8aa3b, v135
	v_mul_f32_e32 v132, v240, v136
	v_exp_f32_e32 v135, v135
	v_add_f32_e32 v136, v83, v139
	v_mul_f32_e32 v136, 0xbfb8aa3b, v136
	v_exp_f32_e32 v136, v136

	v_add_f32_e32 v135, 1.0, v135

	v_rcp_f32_e32 v135, v135
	v_mul_f32_e32 v133, v241, v133
	v_add_f32_e32 v134, 1.0, v136
	v_rcp_f32_e32 v136, v134


	v_mul_f32_e32 v134, v242, v135


	v_mul_f32_e32 v135, v243, v136
	v_add_f32_e32 v136, v80, v140
	v_mul_f32_e32 v136, 0xbfb8aa3b, v136
	v_exp_f32_e32 v136, v136
	v_add_f32_e32 v137, v81, v141
	v_mul_f32_e32 v137, 0xbfb8aa3b, v137
	v_exp_f32_e32 v137, v137
	v_add_f32_e32 v136, 1.0, v136
	v_rcp_f32_e32 v136, v136
	ds_write_b128 v153, v[132:135] offset:8192
	v_add_f32_e32 v132, 1.0, v137
	v_rcp_f32_e32 v133, v132

	v_add_f32_e32 v135, v82, v142

	v_mul_f32_e32 v135, 0xbfb8aa3b, v135
	v_mul_f32_e32 v132, v240, v136
	v_exp_f32_e32 v135, v135
	v_add_f32_e32 v136, v83, v143
	v_mul_f32_e32 v136, 0xbfb8aa3b, v136
	v_exp_f32_e32 v136, v136

	v_add_f32_e32 v135, 1.0, v135

	v_rcp_f32_e32 v135, v135
	v_mul_f32_e32 v133, v241, v133
	v_add_f32_e32 v134, 1.0, v136
	v_rcp_f32_e32 v136, v134

	v_exp_f32_e32 v130, v130
	v_add_f32_e32 v131, v87, v131

	v_rcp_f32_e32 v128, v128
	v_mul_f32_e32 v131, 0xbfb8aa3b, v131
	v_mul_f32_e32 v134, v242, v135

	v_add_f32_e32 v129, 1.0, v129
	v_exp_f32_e32 v131, v131

	v_rcp_f32_e32 v129, v129
	v_add_f32_e32 v124, v84, v124
	v_mul_f32_e32 v135, v243, v136
	v_add_f32_e32 v130, 1.0, v130
	v_mul_f32_e32 v124, 0xbfb8aa3b, v124
	ds_write_b128 v153, v[132:135] offset:12288

	v_rcp_f32_e32 v130, v130
	v_exp_f32_e32 v124, v124
	v_add_f32_e32 v125, v85, v125
	s_nop 0

	v_add_f32_e32 v131, 1.0, v131
	v_mul_f32_e32 v125, 0xbfb8aa3b, v125
	v_mul_f32_e32 v128, v244, v128

	v_rcp_f32_e32 v131, v131
	v_exp_f32_e32 v125, v125
	v_add_f32_e32 v126, v86, v126

	v_mul_f32_e32 v126, 0xbfb8aa3b, v126
	v_mul_f32_e32 v129, v245, v129

	v_add_f32_e32 v124, 1.0, v124
	v_exp_f32_e32 v126, v126
	v_add_f32_e32 v127, v87, v127

	v_rcp_f32_e32 v124, v124
	v_mul_f32_e32 v127, 0xbfb8aa3b, v127
	v_mul_f32_e32 v130, v246, v130

	v_add_f32_e32 v125, 1.0, v125
	v_exp_f32_e32 v127, v127

	v_rcp_f32_e32 v125, v125
	v_add_f32_e32 v120, v84, v120
	v_mul_f32_e32 v131, v247, v131
	v_add_f32_e32 v126, 1.0, v126
	v_mul_f32_e32 v120, 0xbfb8aa3b, v120
	ds_write_b128 v153, v[128:131] offset:64

	v_rcp_f32_e32 v126, v126
	v_exp_f32_e32 v120, v120
	v_add_f32_e32 v121, v85, v121

	v_add_f32_e32 v127, 1.0, v127
	v_mul_f32_e32 v121, 0xbfb8aa3b, v121
	v_mul_f32_e32 v124, v244, v124

	v_rcp_f32_e32 v127, v127
	v_exp_f32_e32 v121, v121
	v_add_f32_e32 v122, v86, v122

	v_mul_f32_e32 v122, 0xbfb8aa3b, v122
	v_mul_f32_e32 v125, v245, v125

	v_add_f32_e32 v120, 1.0, v120
	v_exp_f32_e32 v122, v122
	v_add_f32_e32 v123, v87, v123

	v_rcp_f32_e32 v120, v120
	v_mul_f32_e32 v123, 0xbfb8aa3b, v123
	v_mul_f32_e32 v126, v246, v126

	v_add_f32_e32 v121, 1.0, v121
	v_exp_f32_e32 v123, v123

	v_rcp_f32_e32 v121, v121
	v_add_f32_e32 v116, v84, v116
	v_mul_f32_e32 v127, v247, v127
	v_add_f32_e32 v122, 1.0, v122
	v_mul_f32_e32 v116, 0xbfb8aa3b, v116
	ds_write_b128 v153, v[124:127] offset:4160

	v_rcp_f32_e32 v122, v122
	v_exp_f32_e32 v116, v116
	v_add_f32_e32 v117, v85, v117

	v_add_f32_e32 v123, 1.0, v123
	v_mul_f32_e32 v117, 0xbfb8aa3b, v117
	v_mul_f32_e32 v120, v244, v120

	v_rcp_f32_e32 v123, v123
	v_exp_f32_e32 v117, v117
	v_add_f32_e32 v118, v86, v118

	v_mul_f32_e32 v118, 0xbfb8aa3b, v118
	v_mul_f32_e32 v121, v245, v121

	v_add_f32_e32 v116, 1.0, v116
	v_exp_f32_e32 v118, v118
	v_add_f32_e32 v119, v87, v119

	v_rcp_f32_e32 v116, v116
	v_mul_f32_e32 v119, 0xbfb8aa3b, v119
	v_mul_f32_e32 v122, v246, v122

	v_add_f32_e32 v117, 1.0, v117
	v_exp_f32_e32 v119, v119

	v_rcp_f32_e32 v117, v117
	v_mul_f32_e32 v123, v247, v123
	v_add_f32_e32 v118, 1.0, v118
	ds_write_b128 v153, v[120:123] offset:8256

	v_rcp_f32_e32 v118, v118

	v_add_f32_e32 v119, 1.0, v119
	v_mul_f32_e32 v116, v244, v116

	v_rcp_f32_e32 v119, v119

	v_mul_f32_e32 v117, v245, v117


	v_mul_f32_e32 v118, v246, v118


	v_mul_f32_e32 v119, v247, v119
	v_lshlrev_b32_e32 v133, 2, v152
	ds_write_b128 v153, v[116:119] offset:12352
	v_and_b32_e32 v116, 60, v133
	v_lshlrev_b32_e32 v132, 2, v116
	v_lshlrev_b32_e32 v116, 4, v152
	v_and_b32_e32 v117, 0xffffc000, v116
	v_add_u32_e32 v117, 0, v117
	v_and_b32_e32 v116, 0x3f00, v116
	v_add3_u32 v135, v117, v116, v132
	s_waitcnt lgkmcnt(0)
	s_barrier
	ds_read_b128 v[128:131], v135 offset:25600
	ds_read_b128 v[120:123], v135 offset:58368
	v_add_u32_e32 v134, 0, v132
	v_add_u32_e32 v136, v134, v116
	ds_read_b128 v[124:127], v136
	s_waitcnt lgkmcnt(2)
	v_mul_f32_e32 v116, 0x3fb8aa3b, v128
	v_exp_f32_e32 v116, v116
	v_add_f32_e32 v117, v128, v128
	v_cmp_nlt_f32_e32 vcc, s79, v117
	s_and_saveexec_b64 s[8:9], vcc
	s_xor_b64 s[8:9], exec, s[8:9]
	v_fma_f32 v128, -v116, v116, 1.0
	s_andn2_saveexec_b64 s[8:9], s[8:9]
	v_fmamk_f32 v118, v117, 0x3c088889, v148
	v_fmaak_f32 v118, v117, v118, 0x3e2aaaab
	v_fma_f32 v118, v117, v118, 0.5
	v_fma_f32 v118, v117, v118, 1.0
	v_mul_f32_e64 v128, v118, -v117
	s_or_b64 exec, exec, s[8:9]
	v_mul_f32_e32 v117, 0x3fb8aa3b, v129
	v_exp_f32_e32 v117, v117
	v_add_f32_e32 v118, v129, v129
	v_cmp_nlt_f32_e32 vcc, s79, v118
	s_and_saveexec_b64 s[8:9], vcc
	s_xor_b64 s[8:9], exec, s[8:9]
	v_fma_f32 v129, -v117, v117, 1.0
	s_andn2_saveexec_b64 s[8:9], s[8:9]
	v_fmamk_f32 v119, v118, 0x3c088889, v148
	v_fmaak_f32 v119, v118, v119, 0x3e2aaaab
	v_fma_f32 v119, v118, v119, 0.5
	v_fma_f32 v119, v118, v119, 1.0
	v_mul_f32_e64 v129, v119, -v118
	s_or_b64 exec, exec, s[8:9]
	v_mul_f32_e32 v118, 0x3fb8aa3b, v130
	v_exp_f32_e32 v118, v118
	v_add_f32_e32 v119, v130, v130
	v_cmp_nlt_f32_e32 vcc, s79, v119
	s_and_saveexec_b64 s[8:9], vcc
	s_xor_b64 s[8:9], exec, s[8:9]
	v_fma_f32 v130, -v118, v118, 1.0
	s_andn2_saveexec_b64 s[8:9], s[8:9]
	v_fmamk_f32 v130, v119, 0x3c088889, v148
	v_fmaak_f32 v130, v119, v130, 0x3e2aaaab
	v_fma_f32 v130, v119, v130, 0.5
	v_fma_f32 v130, v119, v130, 1.0
	v_mul_f32_e64 v130, v130, -v119
	s_or_b64 exec, exec, s[8:9]
	v_mul_f32_e32 v119, 0x3fb8aa3b, v131
	v_exp_f32_e32 v119, v119
	v_add_f32_e32 v137, v131, v131
	v_cmp_nlt_f32_e32 vcc, s79, v137
	s_and_saveexec_b64 s[8:9], vcc
	s_xor_b64 s[8:9], exec, s[8:9]
	v_fma_f32 v131, -v119, v119, 1.0
	s_andn2_saveexec_b64 s[8:9], s[8:9]
	v_fmamk_f32 v131, v137, 0x3c088889, v148
	v_fmaak_f32 v131, v137, v131, 0x3e2aaaab
	v_fma_f32 v131, v137, v131, 0.5
	v_fma_f32 v131, v137, v131, 1.0
	v_mul_f32_e64 v131, v131, -v137
	s_or_b64 exec, exec, s[8:9]
	v_max_f32_e32 v128, v128, v128
	v_max_f32_e32 v128, 0, v128
	v_sqrt_f32_e32 v128, v128
	v_max_f32_e32 v129, v129, v129
	v_max_f32_e32 v129, 0, v129
	v_sqrt_f32_e32 v129, v129
	s_waitcnt lgkmcnt(1)
	v_mul_f32_e32 v120, v120, v128
	s_waitcnt lgkmcnt(0)
	v_mul_f32_e32 v120, v124, v120
	v_max_f32_e32 v124, v130, v130
	v_max_f32_e32 v128, v131, v131
	v_max_f32_e32 v124, 0, v124
	v_max_f32_e32 v128, 0, v128
	v_sqrt_f32_e32 v124, v124
	v_sqrt_f32_e32 v128, v128
	v_mul_f32_e32 v121, v121, v129
	v_mul_f32_e32 v121, v125, v121
	v_mul_f32_e32 v122, v122, v124
	v_mul_f32_e32 v123, v123, v128
	v_mul_f32_e32 v122, v126, v122
	v_mul_f32_e32 v123, v127, v123
	ds_write_b128 v135, v[116:119] offset:25600
	ds_write_b128 v135, v[120:123] offset:58368
	v_add_u32_e32 v116, 0x800, v133
	v_and_b32_e32 v117, 0x3ffff000, v116
	v_and_b32_e32 v116, 0xfc0, v116
	v_lshl_add_u32 v117, v117, 2, 0
	v_lshlrev_b32_e32 v116, 2, v116
	v_add3_u32 v137, v117, v116, v132
	ds_read_b128 v[128:131], v137 offset:25600
	ds_read_b128 v[120:123], v137 offset:58368
	v_add_u32_e32 v116, v134, v116
	ds_read_b128 v[124:127], v116
	s_waitcnt lgkmcnt(2)
	v_mul_f32_e32 v116, 0x3fb8aa3b, v128
	v_exp_f32_e32 v116, v116
	v_add_f32_e32 v117, v128, v128
	v_cmp_nlt_f32_e32 vcc, s79, v117
	s_and_saveexec_b64 s[8:9], vcc
	s_xor_b64 s[8:9], exec, s[8:9]
	v_fma_f32 v128, -v116, v116, 1.0
	s_andn2_saveexec_b64 s[8:9], s[8:9]
	v_fmamk_f32 v118, v117, 0x3c088889, v148
	v_fmaak_f32 v118, v117, v118, 0x3e2aaaab
	v_fma_f32 v118, v117, v118, 0.5
	v_fma_f32 v118, v117, v118, 1.0
	v_mul_f32_e64 v128, v118, -v117
	s_or_b64 exec, exec, s[8:9]
	v_mul_f32_e32 v117, 0x3fb8aa3b, v129
	v_exp_f32_e32 v117, v117
	v_add_f32_e32 v118, v129, v129
	v_cmp_nlt_f32_e32 vcc, s79, v118
	s_and_saveexec_b64 s[8:9], vcc
	s_xor_b64 s[8:9], exec, s[8:9]
	v_fma_f32 v129, -v117, v117, 1.0
	s_andn2_saveexec_b64 s[8:9], s[8:9]
	v_fmamk_f32 v119, v118, 0x3c088889, v148
	v_fmaak_f32 v119, v118, v119, 0x3e2aaaab
	v_fma_f32 v119, v118, v119, 0.5
	v_fma_f32 v119, v118, v119, 1.0
	v_mul_f32_e64 v129, v119, -v118
	s_or_b64 exec, exec, s[8:9]
	v_mul_f32_e32 v118, 0x3fb8aa3b, v130
	v_exp_f32_e32 v118, v118
	v_add_f32_e32 v119, v130, v130
	v_cmp_nlt_f32_e32 vcc, s79, v119
	s_and_saveexec_b64 s[8:9], vcc
	s_xor_b64 s[8:9], exec, s[8:9]
	v_fma_f32 v130, -v118, v118, 1.0
	s_andn2_saveexec_b64 s[8:9], s[8:9]
	v_fmamk_f32 v130, v119, 0x3c088889, v148
	v_fmaak_f32 v130, v119, v130, 0x3e2aaaab
	v_fma_f32 v130, v119, v130, 0.5
	v_fma_f32 v130, v119, v130, 1.0
	v_mul_f32_e64 v130, v130, -v119
	s_or_b64 exec, exec, s[8:9]
	v_mul_f32_e32 v119, 0x3fb8aa3b, v131
	v_exp_f32_e32 v119, v119
	v_add_f32_e32 v138, v131, v131
	v_cmp_nlt_f32_e32 vcc, s79, v138
	s_and_saveexec_b64 s[8:9], vcc
	s_xor_b64 s[8:9], exec, s[8:9]
	v_fma_f32 v131, -v119, v119, 1.0
	s_andn2_saveexec_b64 s[8:9], s[8:9]
	v_fmamk_f32 v131, v138, 0x3c088889, v148
	v_fmaak_f32 v131, v138, v131, 0x3e2aaaab
	v_fma_f32 v131, v138, v131, 0.5
	v_fma_f32 v131, v138, v131, 1.0
	v_mul_f32_e64 v131, v131, -v138
	s_or_b64 exec, exec, s[8:9]
	v_max_f32_e32 v128, v128, v128
	v_max_f32_e32 v128, 0, v128
	v_sqrt_f32_e32 v128, v128
	v_max_f32_e32 v129, v129, v129
	v_max_f32_e32 v129, 0, v129
	v_sqrt_f32_e32 v129, v129
	s_waitcnt lgkmcnt(1)
	v_mul_f32_e32 v120, v120, v128
	s_waitcnt lgkmcnt(0)
	v_mul_f32_e32 v120, v124, v120
	v_max_f32_e32 v124, v130, v130
	v_max_f32_e32 v128, v131, v131
	v_max_f32_e32 v124, 0, v124
	v_max_f32_e32 v128, 0, v128
	v_sqrt_f32_e32 v124, v124
	v_sqrt_f32_e32 v128, v128
	v_mul_f32_e32 v121, v121, v129
	v_mul_f32_e32 v121, v125, v121
	v_mul_f32_e32 v122, v122, v124
	v_mul_f32_e32 v123, v123, v128
	v_mul_f32_e32 v122, v126, v122
	v_mul_f32_e32 v123, v127, v123
	ds_write_b128 v137, v[116:119] offset:25600
	ds_write_b128 v137, v[120:123] offset:58368
	ds_read_b128 v[128:131], v135 offset:41984
	v_add_u32_e32 v137, 0xe400, v135
	ds_read_b128 v[120:123], v137 offset:16384
	ds_read_b128 v[124:127], v136
	s_waitcnt lgkmcnt(2)
	v_mul_f32_e32 v116, 0x3fb8aa3b, v128
	v_exp_f32_e32 v116, v116
	v_add_f32_e32 v117, v128, v128
	v_cmp_nlt_f32_e32 vcc, s79, v117
	s_and_saveexec_b64 s[8:9], vcc
	s_xor_b64 s[8:9], exec, s[8:9]
	v_fma_f32 v128, -v116, v116, 1.0
	s_andn2_saveexec_b64 s[8:9], s[8:9]
	v_fmamk_f32 v118, v117, 0x3c088889, v148
	v_fmaak_f32 v118, v117, v118, 0x3e2aaaab
	v_fma_f32 v118, v117, v118, 0.5
	v_fma_f32 v118, v117, v118, 1.0
	v_mul_f32_e64 v128, v118, -v117
	s_or_b64 exec, exec, s[8:9]
	v_mul_f32_e32 v117, 0x3fb8aa3b, v129
	v_exp_f32_e32 v117, v117
	v_add_f32_e32 v118, v129, v129
	v_cmp_nlt_f32_e32 vcc, s79, v118
	s_and_saveexec_b64 s[8:9], vcc
	s_xor_b64 s[8:9], exec, s[8:9]
	v_fma_f32 v129, -v117, v117, 1.0
	s_andn2_saveexec_b64 s[8:9], s[8:9]
	v_fmamk_f32 v119, v118, 0x3c088889, v148
	v_fmaak_f32 v119, v118, v119, 0x3e2aaaab
	v_fma_f32 v119, v118, v119, 0.5
	v_fma_f32 v119, v118, v119, 1.0
	v_mul_f32_e64 v129, v119, -v118
	s_or_b64 exec, exec, s[8:9]
	v_mul_f32_e32 v118, 0x3fb8aa3b, v130
	v_exp_f32_e32 v118, v118
	v_add_f32_e32 v119, v130, v130
	v_cmp_nlt_f32_e32 vcc, s79, v119
	s_and_saveexec_b64 s[8:9], vcc
	s_xor_b64 s[8:9], exec, s[8:9]
	v_fma_f32 v130, -v118, v118, 1.0
	s_andn2_saveexec_b64 s[8:9], s[8:9]
	v_fmamk_f32 v130, v119, 0x3c088889, v148
	v_fmaak_f32 v130, v119, v130, 0x3e2aaaab
	v_fma_f32 v130, v119, v130, 0.5
	v_fma_f32 v130, v119, v130, 1.0
	v_mul_f32_e64 v130, v130, -v119
	s_or_b64 exec, exec, s[8:9]
	v_mul_f32_e32 v119, 0x3fb8aa3b, v131
	v_exp_f32_e32 v119, v119
	v_add_f32_e32 v136, v131, v131
	v_cmp_nlt_f32_e32 vcc, s79, v136
	s_and_saveexec_b64 s[8:9], vcc
	s_xor_b64 s[8:9], exec, s[8:9]
	v_fma_f32 v131, -v119, v119, 1.0
	s_andn2_saveexec_b64 s[8:9], s[8:9]
	v_fmamk_f32 v131, v136, 0x3c088889, v148
	v_fmaak_f32 v131, v136, v131, 0x3e2aaaab
	v_fma_f32 v131, v136, v131, 0.5
	v_fma_f32 v131, v136, v131, 1.0
	v_mul_f32_e64 v131, v131, -v136
	s_or_b64 exec, exec, s[8:9]
	v_max_f32_e32 v128, v128, v128
	v_max_f32_e32 v128, 0, v128
	v_sqrt_f32_e32 v128, v128
	v_max_f32_e32 v129, v129, v129
	v_max_f32_e32 v129, 0, v129
	v_sqrt_f32_e32 v129, v129
	s_waitcnt lgkmcnt(1)
	v_mul_f32_e32 v120, v120, v128
	s_waitcnt lgkmcnt(0)
	v_mul_f32_e32 v120, v124, v120
	v_max_f32_e32 v124, v130, v130
	v_max_f32_e32 v128, v131, v131
	v_max_f32_e32 v124, 0, v124
	v_max_f32_e32 v128, 0, v128
	v_sqrt_f32_e32 v124, v124
	v_sqrt_f32_e32 v128, v128
	v_mul_f32_e32 v121, v121, v129
	v_mul_f32_e32 v121, v125, v121
	v_mul_f32_e32 v122, v122, v124
	v_mul_f32_e32 v123, v123, v128
	v_mul_f32_e32 v122, v126, v122
	v_mul_f32_e32 v123, v127, v123
	ds_write_b128 v135, v[116:119] offset:41984
	ds_write_b128 v137, v[120:123] offset:16384
	v_add_u32_e32 v116, 0x1800, v133
	v_and_b32_e32 v117, 0x3ffff000, v116
	v_and_b32_e32 v116, 0xfc0, v116
	v_lshl_add_u32 v117, v117, 2, 0
	v_lshlrev_b32_e32 v116, 2, v116
	v_add3_u32 v132, v117, v116, v132
	ds_read_b128 v[128:131], v132 offset:25600
	ds_read_b128 v[120:123], v132 offset:58368
	v_add_u32_e32 v116, v134, v116
	ds_read_b128 v[124:127], v116
	s_waitcnt lgkmcnt(2)
	v_mul_f32_e32 v116, 0x3fb8aa3b, v128
	v_exp_f32_e32 v116, v116
	v_add_f32_e32 v117, v128, v128
	v_cmp_nlt_f32_e32 vcc, s79, v117
	s_and_saveexec_b64 s[8:9], vcc
	s_xor_b64 s[8:9], exec, s[8:9]
	v_fma_f32 v128, -v116, v116, 1.0
	s_andn2_saveexec_b64 s[8:9], s[8:9]
	v_fmamk_f32 v118, v117, 0x3c088889, v148
	v_fmaak_f32 v118, v117, v118, 0x3e2aaaab
	v_fma_f32 v118, v117, v118, 0.5
	v_fma_f32 v118, v117, v118, 1.0
	v_mul_f32_e64 v128, v118, -v117
	s_or_b64 exec, exec, s[8:9]
	v_mul_f32_e32 v117, 0x3fb8aa3b, v129
	v_exp_f32_e32 v117, v117
	v_add_f32_e32 v118, v129, v129
	v_cmp_nlt_f32_e32 vcc, s79, v118
	s_and_saveexec_b64 s[8:9], vcc
	s_xor_b64 s[8:9], exec, s[8:9]
	v_fma_f32 v129, -v117, v117, 1.0
	s_andn2_saveexec_b64 s[8:9], s[8:9]
	v_fmamk_f32 v119, v118, 0x3c088889, v148
	v_fmaak_f32 v119, v118, v119, 0x3e2aaaab
	v_fma_f32 v119, v118, v119, 0.5
	v_fma_f32 v119, v118, v119, 1.0
	v_mul_f32_e64 v129, v119, -v118
	s_or_b64 exec, exec, s[8:9]
	v_mul_f32_e32 v118, 0x3fb8aa3b, v130
	v_exp_f32_e32 v118, v118
	v_add_f32_e32 v119, v130, v130
	v_cmp_nlt_f32_e32 vcc, s79, v119
	s_and_saveexec_b64 s[8:9], vcc
	s_xor_b64 s[8:9], exec, s[8:9]
	v_fma_f32 v130, -v118, v118, 1.0
	s_andn2_saveexec_b64 s[8:9], s[8:9]
	v_fmamk_f32 v130, v119, 0x3c088889, v148
	v_fmaak_f32 v130, v119, v130, 0x3e2aaaab
	v_fma_f32 v130, v119, v130, 0.5
	v_fma_f32 v130, v119, v130, 1.0
	v_mul_f32_e64 v130, v130, -v119
	s_or_b64 exec, exec, s[8:9]
	v_mul_f32_e32 v119, 0x3fb8aa3b, v131
	v_exp_f32_e32 v119, v119
	v_add_f32_e32 v133, v131, v131
	v_cmp_nlt_f32_e32 vcc, s79, v133
	s_and_saveexec_b64 s[8:9], vcc
	s_xor_b64 s[8:9], exec, s[8:9]
	v_fma_f32 v131, -v119, v119, 1.0
	s_andn2_saveexec_b64 s[8:9], s[8:9]
	v_fmamk_f32 v131, v133, 0x3c088889, v148
	v_fmaak_f32 v131, v133, v131, 0x3e2aaaab
	v_fma_f32 v131, v133, v131, 0.5
	v_fma_f32 v131, v133, v131, 1.0
	v_mul_f32_e64 v131, v131, -v133
	s_or_b64 exec, exec, s[8:9]
	v_max_f32_e32 v128, v128, v128
	v_max_f32_e32 v128, 0, v128
	v_sqrt_f32_e32 v128, v128
	v_max_f32_e32 v129, v129, v129
	v_max_f32_e32 v129, 0, v129
	v_sqrt_f32_e32 v129, v129
	s_waitcnt lgkmcnt(1)
	v_mul_f32_e32 v120, v120, v128
	v_max_f32_e32 v128, v130, v130
	s_waitcnt lgkmcnt(0)
	v_mul_f32_e32 v120, v124, v120
	v_max_f32_e32 v124, v131, v131
	v_max_f32_e32 v128, 0, v128
	v_max_f32_e32 v124, 0, v124
	v_sqrt_f32_e32 v128, v128
	v_sqrt_f32_e32 v124, v124
	v_ashrrev_i32_e32 v156, 7, v152
	v_mul_f32_e32 v121, v121, v129
	v_mul_f32_e32 v122, v122, v128
	v_and_b32_e32 v172, 0x7f, v152
	v_mul_f32_e32 v123, v123, v124
	v_lshlrev_b32_e32 v146, 4, v156
	v_mul_f32_e32 v121, v125, v121
	v_mul_f32_e32 v122, v126, v122
	v_bfe_u32 v153, v152, 6, 1
	v_mul_f32_e32 v123, v127, v123
	ds_write_b128 v132, v[116:119] offset:25600
	ds_write_b128 v132, v[120:123] offset:58368
	v_and_b32_e32 v154, 63, v152
	v_sub_u32_e32 v116, 63, v146
	v_cmp_gt_u32_e32 vcc, 64, v172
	v_or_b32_e32 v118, 1, v146

	s_nop 0
	v_cndmask_b32_e32 v155, v116, v146, vcc
	v_sub_u32_e32 v119, 63, v118
	v_or_b32_e32 v120, 2, v146

	v_cndmask_b32_e32 v157, v119, v118, vcc
	v_sub_u32_e32 v121, 63, v120
	v_or_b32_e32 v122, 3, v146


	v_cndmask_b32_e32 v158, v121, v120, vcc
	v_sub_u32_e32 v123, 63, v122
	v_or_b32_e32 v124, 4, v146
	s_waitcnt lgkmcnt(0)
	s_barrier
	ds_read2st64_b32 v[116:117], v176 offset0:100 offset1:228


	v_cndmask_b32_e32 v159, v123, v122, vcc
	v_sub_u32_e32 v125, 63, v124
	v_or_b32_e32 v126, 5, v146
	ds_read2st64_b32 v[118:119], v177 offset0:100 offset1:228


	v_cndmask_b32_e32 v160, v125, v124, vcc
	v_sub_u32_e32 v127, 63, v126
	v_or_b32_e32 v128, 6, v146
	ds_read2st64_b32 v[120:121], v178 offset0:100 offset1:228


	v_cndmask_b32_e32 v161, v127, v126, vcc
	v_sub_u32_e32 v129, 63, v128
	v_or_b32_e32 v130, 7, v146
	ds_read2st64_b32 v[122:123], v179 offset0:100 offset1:228


	v_cndmask_b32_e32 v162, v129, v128, vcc
	v_sub_u32_e32 v131, 63, v130
	v_or_b32_e32 v132, 8, v146
	ds_read2st64_b32 v[124:125], v180 offset0:100 offset1:228


	v_cndmask_b32_e32 v163, v131, v130, vcc
	v_sub_u32_e32 v133, 63, v132
	v_or_b32_e32 v134, 9, v146
	ds_read2st64_b32 v[126:127], v181 offset0:100 offset1:228


	v_cndmask_b32_e32 v164, v133, v132, vcc
	v_sub_u32_e32 v135, 63, v134
	v_or_b32_e32 v136, 10, v146
	s_waitcnt lgkmcnt(5)
	v_fma_f32 v173, 0, v116, v117
	ds_read2st64_b32 v[128:129], v182 offset0:100 offset1:228


	v_cndmask_b32_e32 v165, v135, v134, vcc
	v_sub_u32_e32 v137, 63, v136
	v_or_b32_e32 v138, 11, v146
	s_waitcnt lgkmcnt(5)
	v_fma_f32 v173, v173, v118, v119
	ds_read2st64_b32 v[130:131], v183 offset0:100 offset1:228


	v_cndmask_b32_e32 v166, v137, v136, vcc
	v_sub_u32_e32 v139, 63, v138
	v_or_b32_e32 v140, 12, v146
	v_mul_f32_e32 v174, v116, v118
	s_waitcnt lgkmcnt(5)
	v_fma_f32 v173, v173, v120, v121
	ds_read2st64_b32 v[132:133], v184 offset0:100 offset1:228


	v_cndmask_b32_e32 v167, v139, v138, vcc
	v_sub_u32_e32 v141, 63, v140
	v_or_b32_e32 v142, 13, v146
	v_mul_f32_e32 v174, v174, v120
	s_waitcnt lgkmcnt(5)
	v_fma_f32 v173, v173, v122, v123
	ds_read2st64_b32 v[134:135], v185 offset0:100 offset1:228


	v_cndmask_b32_e32 v168, v141, v140, vcc
	v_sub_u32_e32 v143, 63, v142
	v_or_b32_e32 v144, 14, v146
	v_mul_f32_e32 v174, v174, v122
	s_waitcnt lgkmcnt(5)
	v_fma_f32 v173, v173, v124, v125
	ds_read2st64_b32 v[136:137], v186 offset0:100 offset1:228


	v_cndmask_b32_e32 v169, v143, v142, vcc
	v_sub_u32_e32 v145, 63, v144
	v_or_b32_e32 v146, 15, v146
	v_mul_f32_e32 v174, v174, v124
	s_waitcnt lgkmcnt(5)
	v_fma_f32 v173, v173, v126, v127
	ds_read2st64_b32 v[138:139], v187 offset0:100 offset1:228


	v_cndmask_b32_e32 v170, v145, v144, vcc
	v_sub_u32_e32 v171, 63, v146
	v_mul_f32_e32 v174, v174, v126
	s_waitcnt lgkmcnt(5)
	v_fma_f32 v173, v173, v128, v129
	ds_read2st64_b32 v[140:141], v188 offset0:100 offset1:228


	v_cndmask_b32_e32 v171, v171, v146, vcc
	v_mul_f32_e32 v174, v174, v128
	s_waitcnt lgkmcnt(5)
	v_fma_f32 v173, v173, v130, v131
	ds_read2st64_b32 v[142:143], v189 offset0:100 offset1:228


	v_mul_f32_e32 v174, v174, v130
	s_waitcnt lgkmcnt(5)
	v_fma_f32 v173, v173, v132, v133
	ds_read2st64_b32 v[144:145], v190 offset0:100 offset1:228

	v_mul_f32_e32 v174, v174, v132
	s_waitcnt lgkmcnt(5)
	v_fma_f32 v173, v173, v134, v135
	ds_read2st64_b32 v[146:147], v191 offset0:100 offset1:228
	v_mul_f32_e32 v174, v174, v134
	s_waitcnt lgkmcnt(5)
	v_fma_f32 v173, v173, v136, v137
	v_mul_f32_e32 v174, v174, v136
	s_waitcnt lgkmcnt(4)
	v_fma_f32 v173, v173, v138, v139
	v_mul_f32_e32 v174, v174, v138
	s_waitcnt lgkmcnt(3)
	v_fma_f32 v173, v173, v140, v141
	v_mul_f32_e32 v174, v174, v140
	s_waitcnt lgkmcnt(2)
	v_fma_f32 v173, v173, v142, v143
	v_mul_f32_e32 v174, v174, v142
	s_waitcnt lgkmcnt(1)
	v_fma_f32 v173, v173, v144, v145
	v_lshl_add_u32 v152, v152, 2, 0
	v_mul_f32_e32 v174, v174, v144
	s_waitcnt lgkmcnt(0)
	v_fma_f32 v173, v173, v146, v147
	v_add_u32_e32 v175, 0x16400, v152
	v_add_u32_e32 v152, 0x16c00, v152
	v_mul_f32_e32 v174, v174, v146
	ds_write_b32 v152, v173
	v_cmp_lt_i32_e32 vcc, 0, v156
	v_lshl_add_u32 v172, v172, 2, 0
	v_mov_b32_e32 v152, v149
	ds_write_b32 v175, v174
	s_waitcnt lgkmcnt(0)
	s_barrier
	s_and_saveexec_b64 s[8:9], vcc
	s_cbranch_execnz .LBB0_772
	s_or_b64 exec, exec, s[8:9]
	v_cmp_lt_i32_e32 vcc, 1, v156
	s_and_saveexec_b64 s[8:9], vcc
	s_cbranch_execnz .LBB0_773

.LBB0_705:
	v_lshlrev_b32_e32 v2, 16, v68
	v_and_b32_e32 v3, 0xffff0000, v68
	s_nop 0
	v_pk_fma_f32 v[2:3], v[36:37], v[2:3], v[48:49]
	v_lshlrev_b32_e32 v116, 16, v96
	v_and_b32_e32 v117, 0xffff0000, v96
	v_pk_fma_f32 v[2:3], v[8:9], v[116:117], v[2:3]
	v_lshlrev_b32_e32 v116, 16, v104
	v_and_b32_e32 v117, 0xffff0000, v104
	v_pk_fma_f32 v[2:3], v[12:13], v[116:117], v[2:3]
	v_lshlrev_b32_e32 v116, 16, v108
	v_and_b32_e32 v117, 0xffff0000, v108
	v_pk_fma_f32 v[116:117], v[16:17], v[116:117], v[2:3]
	v_lshlrev_b32_e32 v2, 16, v70
	v_and_b32_e32 v3, 0xffff0000, v70
	v_pk_fma_f32 v[2:3], v[24:25], v[2:3], v[44:45]
	v_lshlrev_b32_e32 v118, 16, v98
	v_and_b32_e32 v119, 0xffff0000, v98
	v_pk_fma_f32 v[2:3], v[4:5], v[118:119], v[2:3]
	v_lshlrev_b32_e32 v118, 16, v106
	v_and_b32_e32 v119, 0xffff0000, v106
	v_pk_fma_f32 v[2:3], v[20:21], v[118:119], v[2:3]
	v_lshlrev_b32_e32 v118, 16, v110
	v_and_b32_e32 v119, 0xffff0000, v110
	v_pk_fma_f32 v[120:121], v[32:33], v[118:119], v[2:3]
	v_lshlrev_b32_e32 v2, 16, v69
	v_and_b32_e32 v3, 0xffff0000, v69
	v_pk_fma_f32 v[2:3], v[38:39], v[2:3], v[50:51]
	v_lshlrev_b32_e32 v118, 16, v97
	v_and_b32_e32 v119, 0xffff0000, v97
	v_pk_fma_f32 v[2:3], v[10:11], v[118:119], v[2:3]
	v_lshlrev_b32_e32 v118, 16, v105
	v_and_b32_e32 v119, 0xffff0000, v105
	v_pk_fma_f32 v[2:3], v[14:15], v[118:119], v[2:3]
	v_lshlrev_b32_e32 v118, 16, v109
	v_and_b32_e32 v119, 0xffff0000, v109
	v_pk_fma_f32 v[118:119], v[18:19], v[118:119], v[2:3]
	v_lshlrev_b32_e32 v2, 16, v71
	v_and_b32_e32 v3, 0xffff0000, v71
	v_pk_fma_f32 v[2:3], v[26:27], v[2:3], v[46:47]
	v_lshlrev_b32_e32 v122, 16, v99
	v_and_b32_e32 v123, 0xffff0000, v99
	v_pk_fma_f32 v[2:3], v[6:7], v[122:123], v[2:3]
	v_lshlrev_b32_e32 v122, 16, v107
	v_and_b32_e32 v123, 0xffff0000, v107
	v_mov_b32_e32 v152, v204
	v_pk_fma_f32 v[2:3], v[22:23], v[122:123], v[2:3]
	v_lshlrev_b32_e32 v122, 16, v111
	v_and_b32_e32 v123, 0xffff0000, v111
	v_pk_fma_f32 v[122:123], v[34:35], v[122:123], v[2:3]
	v_lshlrev_b32_e32 v1, 3, v152
	v_ashrrev_i32_e32 v2, 3, v152
	v_and_b32_e32 v1, 56, v1
	v_lshl_add_u32 v151, v2, 8, 0
	v_lshl_add_u32 v3, v1, 2, v151
	ds_write_b128 v3, v[116:119]
	ds_write_b128 v3, v[120:123] offset:16
	v_cvt_pk_bf16_f32 v116, v116, v117
	v_cvt_pk_bf16_f32 v117, v118, v119
	v_cvt_pk_bf16_f32 v118, v120, v121
	v_mul_lo_u32 v120, v2, s1
	v_lshlrev_b32_e32 v121, 1, v1
	v_and_b32_e32 v162, 15, v152
	v_cvt_pk_bf16_f32 v119, v122, v123
	v_add3_u32 v120, v151, v120, v121
	v_and_b32_e32 v153, 48, v152
	ds_write_b128 v120, v[116:119] offset:16384
	v_mul_u32_u24_e32 v116, 0x90, v162
	v_add3_u32 v163, 0, v153, v116
	s_waitcnt lgkmcnt(0)
	s_barrier
	ds_read_b128 v[128:131], v163 offset:20992
	s_waitcnt lgkmcnt(0)
	v_mfma_f32_16x16x32_bf16 v[136:139], v[56:59], v[128:131], 0
	ds_read_b128 v[116:119], v163 offset:16384
	ds_read_b128 v[124:127], v163 offset:18688
	v_cmp_gt_u32_e32 vcc, s49, v152
	s_nop 0
	v_mfma_f32_16x16x32_bf16 v[140:143], v[72:75], v[128:131], 0
	ds_read_b128 v[128:131], v163 offset:23296
	s_waitcnt lgkmcnt(0)
	v_mfma_f32_16x16x32_bf16 v[144:147], v[56:59], v[128:131], 0
	v_mfma_f32_16x16x32_bf16 v[154:157], v[72:75], v[128:131], 0
	ds_read_b128 v[128:131], v163 offset:16448
	v_mfma_f32_16x16x32_bf16 v[120:123], v[56:59], v[116:119], 0
	v_mfma_f32_16x16x32_bf16 v[116:119], v[72:75], v[116:119], 0
	s_waitcnt lgkmcnt(0)
	v_mfma_f32_16x16x32_bf16 v[158:161], v[64:67], v[128:131], v[120:123]
	s_nop 0
	v_mfma_f32_16x16x32_bf16 v[128:131], v[76:79], v[128:131], v[116:119]
	s_nop 3
	ds_read_b128 v[116:119], v163 offset:18752
	v_mfma_f32_16x16x32_bf16 v[132:135], v[56:59], v[124:127], 0
	s_nop 0
	s_nop 0
	v_add_f32_e32 v128, v84, v128
	v_mul_f32_e32 v128, 0xbfb8aa3b, v128
	v_exp_f32_e32 v128, v128
	v_mfma_f32_16x16x32_bf16 v[124:127], v[72:75], v[124:127], 0
	v_add_f32_e32 v129, v85, v129
	v_mul_f32_e32 v129, 0xbfb8aa3b, v129
	v_exp_f32_e32 v129, v129
	s_waitcnt lgkmcnt(0)
	v_mfma_f32_16x16x32_bf16 v[132:135], v[64:67], v[116:119], v[132:135]
	v_add_f32_e32 v130, v86, v130
	v_mul_f32_e32 v130, 0xbfb8aa3b, v130
	v_add_f32_e32 v128, 1.0, v128
	v_mfma_f32_16x16x32_bf16 v[124:127], v[76:79], v[116:119], v[124:127]
	ds_read_b128 v[116:119], v163 offset:21056
	s_nop 2
	v_add_f32_e32 v132, v80, v132
	v_mul_f32_e32 v132, 0xbfb8aa3b, v132
	s_waitcnt lgkmcnt(0)
	v_mfma_f32_16x16x32_bf16 v[136:139], v[64:67], v[116:119], v[136:139]
	v_exp_f32_e32 v132, v132
	v_add_f32_e32 v133, v81, v133
	v_mul_f32_e32 v133, 0xbfb8aa3b, v133
	v_mfma_f32_16x16x32_bf16 v[120:123], v[76:79], v[116:119], v[140:143]
	ds_read_b128 v[116:119], v163 offset:23360
	v_exp_f32_e32 v133, v133
	v_add_f32_e32 v134, v82, v134
	s_waitcnt lgkmcnt(0)
	v_mfma_f32_16x16x32_bf16 v[140:143], v[64:67], v[116:119], v[144:147]
	v_mul_f32_e32 v134, 0xbfb8aa3b, v134
	s_nop 1
	v_mov_b32_e32 v144, s51
	v_mov_b32_e32 v145, s81
	v_cndmask_b32_e32 v144, v144, v145, vcc
	v_lshlrev_b32_e32 v145, 7, v152
	v_and_b32_e32 v145, 0x4000, v145
	v_lshlrev_b32_e32 v146, 8, v162
	v_add3_u32 v144, v144, v145, v146
	v_add_f32_e32 v146, v80, v158
	v_mul_f32_e32 v146, 0xbfb8aa3b, v146
	v_add_f32_e32 v147, v81, v159
	v_exp_f32_e32 v146, v146
	v_mul_f32_e32 v147, 0xbfb8aa3b, v147
	v_exp_f32_e32 v147, v147
	v_lshlrev_b32_e32 v145, 1, v152
	v_and_b32_e32 v145, 0x80, v145
	v_add_f32_e32 v146, 1.0, v146
	v_rcp_f32_e32 v146, v146
	v_add3_u32 v153, v144, v145, v153
	v_add_f32_e32 v144, 1.0, v147
	v_add_f32_e32 v147, v82, v160
	v_mul_f32_e32 v147, 0xbfb8aa3b, v147
	v_mfma_f32_16x16x32_bf16 v[116:119], v[76:79], v[116:119], v[154:157]
	v_rcp_f32_e32 v145, v144
	v_exp_f32_e32 v147, v147

	s_nop 0
	v_add_f32_e32 v154, v83, v161
	v_mul_f32_e32 v154, 0xbfb8aa3b, v154
	v_exp_f32_e32 v154, v154
	s_nop 0

	v_mul_f32_e32 v144, v240, v146

	v_add_f32_e32 v147, 1.0, v147

	v_rcp_f32_e32 v147, v147
	v_mul_f32_e32 v145, v241, v145
	v_add_f32_e32 v146, 1.0, v154
	v_rcp_f32_e32 v154, v146

	v_add_f32_e32 v132, 1.0, v132
	v_exp_f32_e32 v134, v134
	v_add_f32_e32 v135, v83, v135

	v_rcp_f32_e32 v132, v132
	v_mul_f32_e32 v135, 0xbfb8aa3b, v135
	v_mul_f32_e32 v146, v242, v147

	v_add_f32_e32 v133, 1.0, v133
	v_exp_f32_e32 v135, v135

	v_rcp_f32_e32 v133, v133
	v_mul_f32_e32 v147, v243, v154
	v_add_f32_e32 v134, 1.0, v134
	v_add_f32_e32 v136, v80, v136
	ds_write_b128 v153, v[144:147]

	v_rcp_f32_e32 v134, v134
	v_mul_f32_e32 v136, 0xbfb8aa3b, v136

	v_add_f32_e32 v135, 1.0, v135
	v_exp_f32_e32 v136, v136
	v_mul_f32_e32 v132, v240, v132

	v_rcp_f32_e32 v135, v135

	v_add_f32_e32 v137, v81, v137
	v_mul_f32_e32 v133, v241, v133

	v_mul_f32_e32 v137, 0xbfb8aa3b, v137

	v_exp_f32_e32 v137, v137
	v_add_f32_e32 v136, 1.0, v136
	v_mul_f32_e32 v134, v242, v134

	v_rcp_f32_e32 v136, v136

	v_mul_f32_e32 v135, v243, v135
	ds_write_b128 v153, v[132:135] offset:4096
	v_add_f32_e32 v132, 1.0, v137
	v_rcp_f32_e32 v133, v132

	v_add_f32_e32 v135, v82, v138

	v_mul_f32_e32 v135, 0xbfb8aa3b, v135
	v_mul_f32_e32 v132, v240, v136
	v_exp_f32_e32 v135, v135
	v_add_f32_e32 v136, v83, v139
	v_mul_f32_e32 v136, 0xbfb8aa3b, v136
	v_exp_f32_e32 v136, v136

	v_add_f32_e32 v135, 1.0, v135

	v_rcp_f32_e32 v135, v135
	v_mul_f32_e32 v133, v241, v133
	v_add_f32_e32 v134, 1.0, v136
	v_rcp_f32_e32 v136, v134


	v_mul_f32_e32 v134, v242, v135


	v_mul_f32_e32 v135, v243, v136
	v_add_f32_e32 v136, v80, v140
	v_mul_f32_e32 v136, 0xbfb8aa3b, v136
	v_exp_f32_e32 v136, v136
	v_add_f32_e32 v137, v81, v141
	v_mul_f32_e32 v137, 0xbfb8aa3b, v137
	v_exp_f32_e32 v137, v137
	v_add_f32_e32 v136, 1.0, v136
	v_rcp_f32_e32 v136, v136
	ds_write_b128 v153, v[132:135] offset:8192
	v_add_f32_e32 v132, 1.0, v137
	v_rcp_f32_e32 v133, v132

	v_add_f32_e32 v135, v82, v142

	v_mul_f32_e32 v135, 0xbfb8aa3b, v135
	v_mul_f32_e32 v132, v240, v136
	v_exp_f32_e32 v135, v135
	v_add_f32_e32 v136, v83, v143
	v_mul_f32_e32 v136, 0xbfb8aa3b, v136
	v_exp_f32_e32 v136, v136

	v_add_f32_e32 v135, 1.0, v135

	v_rcp_f32_e32 v135, v135
	v_mul_f32_e32 v133, v241, v133
	v_add_f32_e32 v134, 1.0, v136
	v_rcp_f32_e32 v136, v134

	v_exp_f32_e32 v130, v130
	v_add_f32_e32 v131, v87, v131

	v_rcp_f32_e32 v128, v128
	v_mul_f32_e32 v131, 0xbfb8aa3b, v131
	v_mul_f32_e32 v134, v242, v135

	v_add_f32_e32 v129, 1.0, v129
	v_exp_f32_e32 v131, v131

	v_rcp_f32_e32 v129, v129
	v_add_f32_e32 v124, v84, v124
	v_mul_f32_e32 v135, v243, v136
	v_add_f32_e32 v130, 1.0, v130
	v_mul_f32_e32 v124, 0xbfb8aa3b, v124
	ds_write_b128 v153, v[132:135] offset:12288

	v_rcp_f32_e32 v130, v130
	v_exp_f32_e32 v124, v124
	v_add_f32_e32 v125, v85, v125
	s_nop 0

	v_add_f32_e32 v131, 1.0, v131
	v_mul_f32_e32 v125, 0xbfb8aa3b, v125
	v_mul_f32_e32 v128, v244, v128

	v_rcp_f32_e32 v131, v131
	v_exp_f32_e32 v125, v125
	v_add_f32_e32 v126, v86, v126

	v_mul_f32_e32 v126, 0xbfb8aa3b, v126
	v_mul_f32_e32 v129, v245, v129

	v_add_f32_e32 v124, 1.0, v124
	v_exp_f32_e32 v126, v126
	v_add_f32_e32 v127, v87, v127

	v_rcp_f32_e32 v124, v124
	v_mul_f32_e32 v127, 0xbfb8aa3b, v127
	v_mul_f32_e32 v130, v246, v130

	v_add_f32_e32 v125, 1.0, v125
	v_exp_f32_e32 v127, v127

	v_rcp_f32_e32 v125, v125
	v_add_f32_e32 v120, v84, v120
	v_mul_f32_e32 v131, v247, v131
	v_add_f32_e32 v126, 1.0, v126
	v_mul_f32_e32 v120, 0xbfb8aa3b, v120
	ds_write_b128 v153, v[128:131] offset:64

	v_rcp_f32_e32 v126, v126
	v_exp_f32_e32 v120, v120
	v_add_f32_e32 v121, v85, v121

	v_add_f32_e32 v127, 1.0, v127
	v_mul_f32_e32 v121, 0xbfb8aa3b, v121
	v_mul_f32_e32 v124, v244, v124

	v_rcp_f32_e32 v127, v127
	v_exp_f32_e32 v121, v121
	v_add_f32_e32 v122, v86, v122

	v_mul_f32_e32 v122, 0xbfb8aa3b, v122
	v_mul_f32_e32 v125, v245, v125

	v_add_f32_e32 v120, 1.0, v120
	v_exp_f32_e32 v122, v122
	v_add_f32_e32 v123, v87, v123

	v_rcp_f32_e32 v120, v120
	v_mul_f32_e32 v123, 0xbfb8aa3b, v123
	v_mul_f32_e32 v126, v246, v126

	v_add_f32_e32 v121, 1.0, v121
	v_exp_f32_e32 v123, v123

	v_rcp_f32_e32 v121, v121
	v_add_f32_e32 v116, v84, v116
	v_mul_f32_e32 v127, v247, v127
	v_add_f32_e32 v122, 1.0, v122
	v_mul_f32_e32 v116, 0xbfb8aa3b, v116
	ds_write_b128 v153, v[124:127] offset:4160

	v_rcp_f32_e32 v122, v122
	v_exp_f32_e32 v116, v116
	v_add_f32_e32 v117, v85, v117

	v_add_f32_e32 v123, 1.0, v123
	v_mul_f32_e32 v117, 0xbfb8aa3b, v117
	v_mul_f32_e32 v120, v244, v120

	v_rcp_f32_e32 v123, v123
	v_exp_f32_e32 v117, v117
	v_add_f32_e32 v118, v86, v118

	v_mul_f32_e32 v118, 0xbfb8aa3b, v118
	v_mul_f32_e32 v121, v245, v121

	v_add_f32_e32 v116, 1.0, v116
	v_exp_f32_e32 v118, v118
	v_add_f32_e32 v119, v87, v119

	v_rcp_f32_e32 v116, v116
	v_mul_f32_e32 v119, 0xbfb8aa3b, v119
	v_mul_f32_e32 v122, v246, v122

	v_add_f32_e32 v117, 1.0, v117
	v_exp_f32_e32 v119, v119

	v_rcp_f32_e32 v117, v117
	v_mul_f32_e32 v123, v247, v123
	v_add_f32_e32 v118, 1.0, v118
	ds_write_b128 v153, v[120:123] offset:8256

	v_rcp_f32_e32 v118, v118

	v_add_f32_e32 v119, 1.0, v119
	v_mul_f32_e32 v116, v244, v116

	v_rcp_f32_e32 v119, v119

	v_mul_f32_e32 v117, v245, v117


	v_mul_f32_e32 v118, v246, v118


	v_mul_f32_e32 v119, v247, v119
	v_lshlrev_b32_e32 v133, 2, v152
	ds_write_b128 v153, v[116:119] offset:12352
	v_and_b32_e32 v116, 60, v133
	v_lshlrev_b32_e32 v132, 2, v116
	v_lshlrev_b32_e32 v116, 4, v152
	v_and_b32_e32 v117, 0xffffc000, v116
	v_add_u32_e32 v117, 0, v117
	v_and_b32_e32 v116, 0x3f00, v116
	v_add3_u32 v135, v117, v116, v132
	s_waitcnt lgkmcnt(0)
	s_barrier
	ds_read_b128 v[128:131], v135 offset:25600
	ds_read_b128 v[120:123], v135 offset:58368
	v_add_u32_e32 v134, 0, v132
	v_add_u32_e32 v136, v134, v116
	ds_read_b128 v[124:127], v136
	s_waitcnt lgkmcnt(2)
	v_mul_f32_e32 v116, 0x3fb8aa3b, v128
	v_exp_f32_e32 v116, v116
	v_add_f32_e32 v117, v128, v128
	v_cmp_nlt_f32_e32 vcc, s79, v117
	s_and_saveexec_b64 s[6:7], vcc
	s_xor_b64 s[6:7], exec, s[6:7]
	v_fma_f32 v128, -v116, v116, 1.0
	s_andn2_saveexec_b64 s[6:7], s[6:7]
	v_fmamk_f32 v118, v117, 0x3c088889, v148
	v_fmaak_f32 v118, v117, v118, 0x3e2aaaab
	v_fma_f32 v118, v117, v118, 0.5
	v_fma_f32 v118, v117, v118, 1.0
	v_mul_f32_e64 v128, v118, -v117
	s_or_b64 exec, exec, s[6:7]
	v_mul_f32_e32 v117, 0x3fb8aa3b, v129
	v_exp_f32_e32 v117, v117
	v_add_f32_e32 v118, v129, v129
	v_cmp_nlt_f32_e32 vcc, s79, v118
	s_and_saveexec_b64 s[6:7], vcc
	s_xor_b64 s[6:7], exec, s[6:7]
	v_fma_f32 v129, -v117, v117, 1.0
	s_andn2_saveexec_b64 s[6:7], s[6:7]
	v_fmamk_f32 v119, v118, 0x3c088889, v148
	v_fmaak_f32 v119, v118, v119, 0x3e2aaaab
	v_fma_f32 v119, v118, v119, 0.5
	v_fma_f32 v119, v118, v119, 1.0
	v_mul_f32_e64 v129, v119, -v118
	s_or_b64 exec, exec, s[6:7]
	v_mul_f32_e32 v118, 0x3fb8aa3b, v130
	v_exp_f32_e32 v118, v118
	v_add_f32_e32 v119, v130, v130
	v_cmp_nlt_f32_e32 vcc, s79, v119
	s_and_saveexec_b64 s[6:7], vcc
	s_xor_b64 s[6:7], exec, s[6:7]
	v_fma_f32 v130, -v118, v118, 1.0
	s_andn2_saveexec_b64 s[6:7], s[6:7]
	v_fmamk_f32 v130, v119, 0x3c088889, v148
	v_fmaak_f32 v130, v119, v130, 0x3e2aaaab
	v_fma_f32 v130, v119, v130, 0.5
	v_fma_f32 v130, v119, v130, 1.0
	v_mul_f32_e64 v130, v130, -v119
	s_or_b64 exec, exec, s[6:7]
	v_mul_f32_e32 v119, 0x3fb8aa3b, v131
	v_exp_f32_e32 v119, v119
	v_add_f32_e32 v137, v131, v131
	v_cmp_nlt_f32_e32 vcc, s79, v137
	s_and_saveexec_b64 s[6:7], vcc
	s_xor_b64 s[6:7], exec, s[6:7]
	v_fma_f32 v131, -v119, v119, 1.0
	s_andn2_saveexec_b64 s[6:7], s[6:7]
	v_fmamk_f32 v131, v137, 0x3c088889, v148
	v_fmaak_f32 v131, v137, v131, 0x3e2aaaab
	v_fma_f32 v131, v137, v131, 0.5
	v_fma_f32 v131, v137, v131, 1.0
	v_mul_f32_e64 v131, v131, -v137
	s_or_b64 exec, exec, s[6:7]
	v_max_f32_e32 v128, v128, v128
	v_max_f32_e32 v128, 0, v128
	v_sqrt_f32_e32 v128, v128
	v_max_f32_e32 v129, v129, v129
	v_max_f32_e32 v129, 0, v129
	v_sqrt_f32_e32 v129, v129
	s_waitcnt lgkmcnt(1)
	v_mul_f32_e32 v120, v120, v128
	s_waitcnt lgkmcnt(0)
	v_mul_f32_e32 v120, v124, v120
	v_max_f32_e32 v124, v130, v130
	v_max_f32_e32 v128, v131, v131
	v_max_f32_e32 v124, 0, v124
	v_max_f32_e32 v128, 0, v128
	v_sqrt_f32_e32 v124, v124
	v_sqrt_f32_e32 v128, v128
	v_mul_f32_e32 v121, v121, v129
	v_mul_f32_e32 v121, v125, v121
	v_mul_f32_e32 v122, v122, v124
	v_mul_f32_e32 v123, v123, v128
	v_mul_f32_e32 v122, v126, v122
	v_mul_f32_e32 v123, v127, v123
	ds_write_b128 v135, v[116:119] offset:25600
	ds_write_b128 v135, v[120:123] offset:58368
	v_add_u32_e32 v116, 0x800, v133
	v_and_b32_e32 v117, 0x3ffff000, v116
	v_and_b32_e32 v116, 0xfc0, v116
	v_lshl_add_u32 v117, v117, 2, 0
	v_lshlrev_b32_e32 v116, 2, v116
	v_add3_u32 v137, v117, v116, v132
	ds_read_b128 v[128:131], v137 offset:25600
	ds_read_b128 v[120:123], v137 offset:58368
	v_add_u32_e32 v116, v134, v116
	ds_read_b128 v[124:127], v116
	s_waitcnt lgkmcnt(2)
	v_mul_f32_e32 v116, 0x3fb8aa3b, v128
	v_exp_f32_e32 v116, v116
	v_add_f32_e32 v117, v128, v128
	v_cmp_nlt_f32_e32 vcc, s79, v117
	s_and_saveexec_b64 s[6:7], vcc
	s_xor_b64 s[6:7], exec, s[6:7]
	v_fma_f32 v128, -v116, v116, 1.0
	s_andn2_saveexec_b64 s[6:7], s[6:7]
	v_fmamk_f32 v118, v117, 0x3c088889, v148
	v_fmaak_f32 v118, v117, v118, 0x3e2aaaab
	v_fma_f32 v118, v117, v118, 0.5
	v_fma_f32 v118, v117, v118, 1.0
	v_mul_f32_e64 v128, v118, -v117
	s_or_b64 exec, exec, s[6:7]
	v_mul_f32_e32 v117, 0x3fb8aa3b, v129
	v_exp_f32_e32 v117, v117
	v_add_f32_e32 v118, v129, v129
	v_cmp_nlt_f32_e32 vcc, s79, v118
	s_and_saveexec_b64 s[6:7], vcc
	s_xor_b64 s[6:7], exec, s[6:7]
	v_fma_f32 v129, -v117, v117, 1.0
	s_andn2_saveexec_b64 s[6:7], s[6:7]
	v_fmamk_f32 v119, v118, 0x3c088889, v148
	v_fmaak_f32 v119, v118, v119, 0x3e2aaaab
	v_fma_f32 v119, v118, v119, 0.5
	v_fma_f32 v119, v118, v119, 1.0
	v_mul_f32_e64 v129, v119, -v118
	s_or_b64 exec, exec, s[6:7]
	v_mul_f32_e32 v118, 0x3fb8aa3b, v130
	v_exp_f32_e32 v118, v118
	v_add_f32_e32 v119, v130, v130
	v_cmp_nlt_f32_e32 vcc, s79, v119
	s_and_saveexec_b64 s[6:7], vcc
	s_xor_b64 s[6:7], exec, s[6:7]
	v_fma_f32 v130, -v118, v118, 1.0
	s_andn2_saveexec_b64 s[6:7], s[6:7]
	v_fmamk_f32 v130, v119, 0x3c088889, v148
	v_fmaak_f32 v130, v119, v130, 0x3e2aaaab
	v_fma_f32 v130, v119, v130, 0.5
	v_fma_f32 v130, v119, v130, 1.0
	v_mul_f32_e64 v130, v130, -v119
	s_or_b64 exec, exec, s[6:7]
	v_mul_f32_e32 v119, 0x3fb8aa3b, v131
	v_exp_f32_e32 v119, v119
	v_add_f32_e32 v138, v131, v131
	v_cmp_nlt_f32_e32 vcc, s79, v138
	s_and_saveexec_b64 s[6:7], vcc
	s_xor_b64 s[6:7], exec, s[6:7]
	v_fma_f32 v131, -v119, v119, 1.0
	s_andn2_saveexec_b64 s[6:7], s[6:7]
	v_fmamk_f32 v131, v138, 0x3c088889, v148
	v_fmaak_f32 v131, v138, v131, 0x3e2aaaab
	v_fma_f32 v131, v138, v131, 0.5
	v_fma_f32 v131, v138, v131, 1.0
	v_mul_f32_e64 v131, v131, -v138
	s_or_b64 exec, exec, s[6:7]
	v_max_f32_e32 v128, v128, v128
	v_max_f32_e32 v128, 0, v128
	v_sqrt_f32_e32 v128, v128
	v_max_f32_e32 v129, v129, v129
	v_max_f32_e32 v129, 0, v129
	v_sqrt_f32_e32 v129, v129
	s_waitcnt lgkmcnt(1)
	v_mul_f32_e32 v120, v120, v128
	s_waitcnt lgkmcnt(0)
	v_mul_f32_e32 v120, v124, v120
	v_max_f32_e32 v124, v130, v130
	v_max_f32_e32 v128, v131, v131
	v_max_f32_e32 v124, 0, v124
	v_max_f32_e32 v128, 0, v128
	v_sqrt_f32_e32 v124, v124
	v_sqrt_f32_e32 v128, v128
	v_mul_f32_e32 v121, v121, v129
	v_mul_f32_e32 v121, v125, v121
	v_mul_f32_e32 v122, v122, v124
	v_mul_f32_e32 v123, v123, v128
	v_mul_f32_e32 v122, v126, v122
	v_mul_f32_e32 v123, v127, v123
	ds_write_b128 v137, v[116:119] offset:25600
	ds_write_b128 v137, v[120:123] offset:58368
	ds_read_b128 v[128:131], v135 offset:41984
	v_add_u32_e32 v137, 0xe400, v135
	ds_read_b128 v[120:123], v137 offset:16384
	ds_read_b128 v[124:127], v136
	s_waitcnt lgkmcnt(2)
	v_mul_f32_e32 v116, 0x3fb8aa3b, v128
	v_exp_f32_e32 v116, v116
	v_add_f32_e32 v117, v128, v128
	v_cmp_nlt_f32_e32 vcc, s79, v117
	s_and_saveexec_b64 s[6:7], vcc
	s_xor_b64 s[6:7], exec, s[6:7]
	v_fma_f32 v128, -v116, v116, 1.0
	s_andn2_saveexec_b64 s[6:7], s[6:7]
	v_fmamk_f32 v118, v117, 0x3c088889, v148
	v_fmaak_f32 v118, v117, v118, 0x3e2aaaab
	v_fma_f32 v118, v117, v118, 0.5
	v_fma_f32 v118, v117, v118, 1.0
	v_mul_f32_e64 v128, v118, -v117
	s_or_b64 exec, exec, s[6:7]
	v_mul_f32_e32 v117, 0x3fb8aa3b, v129
	v_exp_f32_e32 v117, v117
	v_add_f32_e32 v118, v129, v129
	v_cmp_nlt_f32_e32 vcc, s79, v118
	s_and_saveexec_b64 s[6:7], vcc
	s_xor_b64 s[6:7], exec, s[6:7]
	v_fma_f32 v129, -v117, v117, 1.0
	s_andn2_saveexec_b64 s[6:7], s[6:7]
	v_fmamk_f32 v119, v118, 0x3c088889, v148
	v_fmaak_f32 v119, v118, v119, 0x3e2aaaab
	v_fma_f32 v119, v118, v119, 0.5
	v_fma_f32 v119, v118, v119, 1.0
	v_mul_f32_e64 v129, v119, -v118
	s_or_b64 exec, exec, s[6:7]
	v_mul_f32_e32 v118, 0x3fb8aa3b, v130
	v_exp_f32_e32 v118, v118
	v_add_f32_e32 v119, v130, v130
	v_cmp_nlt_f32_e32 vcc, s79, v119
	s_and_saveexec_b64 s[6:7], vcc
	s_xor_b64 s[6:7], exec, s[6:7]
	v_fma_f32 v130, -v118, v118, 1.0
	s_andn2_saveexec_b64 s[6:7], s[6:7]
	v_fmamk_f32 v130, v119, 0x3c088889, v148
	v_fmaak_f32 v130, v119, v130, 0x3e2aaaab
	v_fma_f32 v130, v119, v130, 0.5
	v_fma_f32 v130, v119, v130, 1.0
	v_mul_f32_e64 v130, v130, -v119
	s_or_b64 exec, exec, s[6:7]
	v_mul_f32_e32 v119, 0x3fb8aa3b, v131
	v_exp_f32_e32 v119, v119
	v_add_f32_e32 v136, v131, v131
	v_cmp_nlt_f32_e32 vcc, s79, v136
	s_and_saveexec_b64 s[6:7], vcc
	s_xor_b64 s[6:7], exec, s[6:7]
	v_fma_f32 v131, -v119, v119, 1.0
	s_andn2_saveexec_b64 s[6:7], s[6:7]
	v_fmamk_f32 v131, v136, 0x3c088889, v148
	v_fmaak_f32 v131, v136, v131, 0x3e2aaaab
	v_fma_f32 v131, v136, v131, 0.5
	v_fma_f32 v131, v136, v131, 1.0
	v_mul_f32_e64 v131, v131, -v136
	s_or_b64 exec, exec, s[6:7]
	v_max_f32_e32 v128, v128, v128
	v_max_f32_e32 v128, 0, v128
	v_sqrt_f32_e32 v128, v128
	v_max_f32_e32 v129, v129, v129
	v_max_f32_e32 v129, 0, v129
	v_sqrt_f32_e32 v129, v129
	s_waitcnt lgkmcnt(1)
	v_mul_f32_e32 v120, v120, v128
	s_waitcnt lgkmcnt(0)
	v_mul_f32_e32 v120, v124, v120
	v_max_f32_e32 v124, v130, v130
	v_max_f32_e32 v128, v131, v131
	v_max_f32_e32 v124, 0, v124
	v_max_f32_e32 v128, 0, v128
	v_sqrt_f32_e32 v124, v124
	v_sqrt_f32_e32 v128, v128
	v_mul_f32_e32 v121, v121, v129
	v_mul_f32_e32 v121, v125, v121
	v_mul_f32_e32 v122, v122, v124
	v_mul_f32_e32 v123, v123, v128
	v_mul_f32_e32 v122, v126, v122
	v_mul_f32_e32 v123, v127, v123
	ds_write_b128 v135, v[116:119] offset:41984
	ds_write_b128 v137, v[120:123] offset:16384
	v_add_u32_e32 v116, 0x1800, v133
	v_and_b32_e32 v117, 0x3ffff000, v116
	v_and_b32_e32 v116, 0xfc0, v116
	v_lshl_add_u32 v117, v117, 2, 0
	v_lshlrev_b32_e32 v116, 2, v116
	v_add3_u32 v132, v117, v116, v132
	ds_read_b128 v[128:131], v132 offset:25600
	ds_read_b128 v[120:123], v132 offset:58368
	v_add_u32_e32 v116, v134, v116
	ds_read_b128 v[124:127], v116
	s_waitcnt lgkmcnt(2)
	v_mul_f32_e32 v116, 0x3fb8aa3b, v128
	v_exp_f32_e32 v116, v116
	v_add_f32_e32 v117, v128, v128
	v_cmp_nlt_f32_e32 vcc, s79, v117
	s_and_saveexec_b64 s[6:7], vcc
	s_xor_b64 s[6:7], exec, s[6:7]
	v_fma_f32 v128, -v116, v116, 1.0
	s_andn2_saveexec_b64 s[6:7], s[6:7]
	v_fmamk_f32 v118, v117, 0x3c088889, v148
	v_fmaak_f32 v118, v117, v118, 0x3e2aaaab
	v_fma_f32 v118, v117, v118, 0.5
	v_fma_f32 v118, v117, v118, 1.0
	v_mul_f32_e64 v128, v118, -v117
	s_or_b64 exec, exec, s[6:7]
	v_mul_f32_e32 v117, 0x3fb8aa3b, v129
	v_exp_f32_e32 v117, v117
	v_add_f32_e32 v118, v129, v129
	v_cmp_nlt_f32_e32 vcc, s79, v118
	s_and_saveexec_b64 s[6:7], vcc
	s_xor_b64 s[6:7], exec, s[6:7]
	v_fma_f32 v129, -v117, v117, 1.0
	s_andn2_saveexec_b64 s[6:7], s[6:7]
	v_fmamk_f32 v119, v118, 0x3c088889, v148
	v_fmaak_f32 v119, v118, v119, 0x3e2aaaab
	v_fma_f32 v119, v118, v119, 0.5
	v_fma_f32 v119, v118, v119, 1.0
	v_mul_f32_e64 v129, v119, -v118
	s_or_b64 exec, exec, s[6:7]
	v_mul_f32_e32 v118, 0x3fb8aa3b, v130
	v_exp_f32_e32 v118, v118
	v_add_f32_e32 v119, v130, v130
	v_cmp_nlt_f32_e32 vcc, s79, v119
	s_and_saveexec_b64 s[6:7], vcc
	s_xor_b64 s[6:7], exec, s[6:7]
	v_fma_f32 v130, -v118, v118, 1.0
	s_andn2_saveexec_b64 s[6:7], s[6:7]
	v_fmamk_f32 v130, v119, 0x3c088889, v148
	v_fmaak_f32 v130, v119, v130, 0x3e2aaaab
	v_fma_f32 v130, v119, v130, 0.5
	v_fma_f32 v130, v119, v130, 1.0
	v_mul_f32_e64 v130, v130, -v119
	s_or_b64 exec, exec, s[6:7]
	v_mul_f32_e32 v119, 0x3fb8aa3b, v131
	v_exp_f32_e32 v119, v119
	v_add_f32_e32 v133, v131, v131
	v_cmp_nlt_f32_e32 vcc, s79, v133
	s_and_saveexec_b64 s[6:7], vcc
	s_xor_b64 s[6:7], exec, s[6:7]
	v_fma_f32 v131, -v119, v119, 1.0
	s_andn2_saveexec_b64 s[6:7], s[6:7]
	v_fmamk_f32 v131, v133, 0x3c088889, v148
	v_fmaak_f32 v131, v133, v131, 0x3e2aaaab
	v_fma_f32 v131, v133, v131, 0.5
	v_fma_f32 v131, v133, v131, 1.0
	v_mul_f32_e64 v131, v131, -v133
	s_or_b64 exec, exec, s[6:7]
	v_max_f32_e32 v128, v128, v128
	v_max_f32_e32 v128, 0, v128
	v_sqrt_f32_e32 v128, v128
	v_max_f32_e32 v129, v129, v129
	v_max_f32_e32 v129, 0, v129
	v_sqrt_f32_e32 v129, v129
	s_waitcnt lgkmcnt(1)
	v_mul_f32_e32 v120, v120, v128
	v_max_f32_e32 v128, v130, v130
	s_waitcnt lgkmcnt(0)
	v_mul_f32_e32 v120, v124, v120
	v_max_f32_e32 v124, v131, v131
	v_max_f32_e32 v128, 0, v128
	v_max_f32_e32 v124, 0, v124
	v_sqrt_f32_e32 v128, v128
	v_sqrt_f32_e32 v124, v124
	v_ashrrev_i32_e32 v156, 7, v152
	v_mul_f32_e32 v121, v121, v129
	v_mul_f32_e32 v122, v122, v128
	v_and_b32_e32 v172, 0x7f, v152
	v_mul_f32_e32 v123, v123, v124
	v_lshlrev_b32_e32 v146, 4, v156
	v_mul_f32_e32 v121, v125, v121
	v_mul_f32_e32 v122, v126, v122
	v_bfe_u32 v153, v152, 6, 1
	v_mul_f32_e32 v123, v127, v123
	ds_write_b128 v132, v[116:119] offset:25600
	ds_write_b128 v132, v[120:123] offset:58368
	v_and_b32_e32 v154, 63, v152
	v_sub_u32_e32 v116, 63, v146
	v_cmp_gt_u32_e32 vcc, 64, v172
	v_or_b32_e32 v118, 1, v146

	s_nop 0
	v_cndmask_b32_e32 v155, v116, v146, vcc
	v_sub_u32_e32 v119, 63, v118
	v_or_b32_e32 v120, 2, v146

	v_cndmask_b32_e32 v157, v119, v118, vcc
	v_sub_u32_e32 v121, 63, v120
	v_or_b32_e32 v122, 3, v146


	v_cndmask_b32_e32 v158, v121, v120, vcc
	v_sub_u32_e32 v123, 63, v122
	v_or_b32_e32 v124, 4, v146
	s_waitcnt lgkmcnt(0)
	s_barrier
	ds_read2st64_b32 v[116:117], v176 offset0:100 offset1:228


	v_cndmask_b32_e32 v159, v123, v122, vcc
	v_sub_u32_e32 v125, 63, v124
	v_or_b32_e32 v126, 5, v146
	ds_read2st64_b32 v[118:119], v177 offset0:100 offset1:228


	v_cndmask_b32_e32 v160, v125, v124, vcc
	v_sub_u32_e32 v127, 63, v126
	v_or_b32_e32 v128, 6, v146
	ds_read2st64_b32 v[120:121], v178 offset0:100 offset1:228


	v_cndmask_b32_e32 v161, v127, v126, vcc
	v_sub_u32_e32 v129, 63, v128
	v_or_b32_e32 v130, 7, v146
	ds_read2st64_b32 v[122:123], v179 offset0:100 offset1:228


	v_cndmask_b32_e32 v162, v129, v128, vcc
	v_sub_u32_e32 v131, 63, v130
	v_or_b32_e32 v132, 8, v146
	ds_read2st64_b32 v[124:125], v180 offset0:100 offset1:228


	v_cndmask_b32_e32 v163, v131, v130, vcc
	v_sub_u32_e32 v133, 63, v132
	v_or_b32_e32 v134, 9, v146
	ds_read2st64_b32 v[126:127], v181 offset0:100 offset1:228


	v_cndmask_b32_e32 v164, v133, v132, vcc
	v_sub_u32_e32 v135, 63, v134
	v_or_b32_e32 v136, 10, v146
	s_waitcnt lgkmcnt(5)
	v_fma_f32 v173, 0, v116, v117
	ds_read2st64_b32 v[128:129], v182 offset0:100 offset1:228


	v_cndmask_b32_e32 v165, v135, v134, vcc
	v_sub_u32_e32 v137, 63, v136
	v_or_b32_e32 v138, 11, v146
	s_waitcnt lgkmcnt(5)
	v_fma_f32 v173, v173, v118, v119
	ds_read2st64_b32 v[130:131], v183 offset0:100 offset1:228


	v_cndmask_b32_e32 v166, v137, v136, vcc
	v_sub_u32_e32 v139, 63, v138
	v_or_b32_e32 v140, 12, v146
	v_mul_f32_e32 v174, v116, v118
	s_waitcnt lgkmcnt(5)
	v_fma_f32 v173, v173, v120, v121
	ds_read2st64_b32 v[132:133], v184 offset0:100 offset1:228


	v_cndmask_b32_e32 v167, v139, v138, vcc
	v_sub_u32_e32 v141, 63, v140
	v_or_b32_e32 v142, 13, v146
	v_mul_f32_e32 v174, v174, v120
	s_waitcnt lgkmcnt(5)
	v_fma_f32 v173, v173, v122, v123
	ds_read2st64_b32 v[134:135], v185 offset0:100 offset1:228


	v_cndmask_b32_e32 v168, v141, v140, vcc
	v_sub_u32_e32 v143, 63, v142
	v_or_b32_e32 v144, 14, v146
	v_mul_f32_e32 v174, v174, v122
	s_waitcnt lgkmcnt(5)
	v_fma_f32 v173, v173, v124, v125
	ds_read2st64_b32 v[136:137], v186 offset0:100 offset1:228


	v_cndmask_b32_e32 v169, v143, v142, vcc
	v_sub_u32_e32 v145, 63, v144
	v_or_b32_e32 v146, 15, v146
	v_mul_f32_e32 v174, v174, v124
	s_waitcnt lgkmcnt(5)
	v_fma_f32 v173, v173, v126, v127
	ds_read2st64_b32 v[138:139], v187 offset0:100 offset1:228


	v_cndmask_b32_e32 v170, v145, v144, vcc
	v_sub_u32_e32 v171, 63, v146
	v_mul_f32_e32 v174, v174, v126
	s_waitcnt lgkmcnt(5)
	v_fma_f32 v173, v173, v128, v129
	ds_read2st64_b32 v[140:141], v188 offset0:100 offset1:228


	v_cndmask_b32_e32 v171, v171, v146, vcc
	v_mul_f32_e32 v174, v174, v128
	s_waitcnt lgkmcnt(5)
	v_fma_f32 v173, v173, v130, v131
	ds_read2st64_b32 v[142:143], v189 offset0:100 offset1:228


	v_mul_f32_e32 v174, v174, v130
	s_waitcnt lgkmcnt(5)
	v_fma_f32 v173, v173, v132, v133
	ds_read2st64_b32 v[144:145], v190 offset0:100 offset1:228

	v_mul_f32_e32 v174, v174, v132
	s_waitcnt lgkmcnt(5)
	v_fma_f32 v173, v173, v134, v135
	ds_read2st64_b32 v[146:147], v191 offset0:100 offset1:228
	v_mul_f32_e32 v174, v174, v134
	s_waitcnt lgkmcnt(5)
	v_fma_f32 v173, v173, v136, v137
	v_mul_f32_e32 v174, v174, v136
	s_waitcnt lgkmcnt(4)
	v_fma_f32 v173, v173, v138, v139
	v_mul_f32_e32 v174, v174, v138
	s_waitcnt lgkmcnt(3)
	v_fma_f32 v173, v173, v140, v141
	v_mul_f32_e32 v174, v174, v140
	s_waitcnt lgkmcnt(2)
	v_fma_f32 v173, v173, v142, v143
	v_mul_f32_e32 v174, v174, v142
	s_waitcnt lgkmcnt(1)
	v_fma_f32 v173, v173, v144, v145
	v_lshl_add_u32 v152, v152, 2, 0
	v_mul_f32_e32 v174, v174, v144
	s_waitcnt lgkmcnt(0)
	v_fma_f32 v173, v173, v146, v147
	v_add_u32_e32 v175, 0x16400, v152
	v_add_u32_e32 v152, 0x16c00, v152
	v_mul_f32_e32 v174, v174, v146
	ds_write_b32 v152, v173
	v_cmp_lt_i32_e32 vcc, 0, v156
	v_lshl_add_u32 v172, v172, 2, 0
	v_mov_b32_e32 v152, v150
	ds_write_b32 v175, v174
	s_waitcnt lgkmcnt(0)
	s_barrier
	s_and_saveexec_b64 s[6:7], vcc
	s_cbranch_execnz .LBB0_774
	s_or_b64 exec, exec, s[6:7]
	v_cmp_lt_i32_e32 vcc, 1, v156
	s_and_saveexec_b64 s[6:7], vcc
	s_cbranch_execnz .LBB0_775
